# OUT GEMM leftover tiles also split into two 128-row half tiles (as DOWN in previous version)
# speedup vs baseline: 1.0076x; 1.0049x over previous
.LBB0_921:
	s_or_b64 exec, exec, s[0:1]
	v_readlane_b32 s2, v253, 0
	s_waitcnt lgkmcnt(0)
	s_barrier
	s_lshr_b32 s25, s24, 11
	s_ashr_i32 s4, s2, 3
	s_lshr_b32 s26, s24, 8
	s_cmp_ge_i32 s4, s26
	s_cbranch_scc1 .LBB0_926
	v_readlane_b32 s0, v254, 45
	v_readlane_b32 s6, v254, 41
	v_readlane_b32 s1, v254, 46
	s_add_u32 s0, s0, 0x2000
	v_readlane_b32 s7, v254, 42
	v_readlane_b32 s8, v253, 36
	s_addc_u32 s1, s1, 0
	s_lshl_b64 s[6:7], s[6:7], 21
	v_readlane_b32 s22, v253, 50
	v_readlane_b32 s23, v253, 51
	s_add_u32 s5, s22, s6
	s_addc_u32 s6, s23, s7
	s_and_b32 s7, s2, 7
	s_mul_i32 s7, s7, s25
	v_readlane_b32 s9, v253, 37
	v_readlane_b32 s10, v253, 38
	v_readlane_b32 s11, v253, 39
	v_readlane_b32 s12, v253, 40
	v_readlane_b32 s13, v253, 41
	v_readlane_b32 s14, v253, 42
	v_readlane_b32 s15, v253, 43
	v_readlane_b32 s16, v253, 44
	v_readlane_b32 s17, v253, 45
	v_readlane_b32 s18, v253, 46
	v_readlane_b32 s19, v253, 47
	v_readlane_b32 s20, v253, 48
	v_readlane_b32 s21, v253, 49
	s_mov_b32 s100, 0
.LBB0_923:
	s_ashr_i32 s2, s4, 31
	s_lshr_b32 s2, s2, 26
	s_add_i32 s2, s4, s2
	s_ashr_i32 s3, s2, 6
	s_lshl_b32 s3, s3, 3
	s_sub_i32 s8, s25, s3
	s_min_i32 s8, s8, 8
	s_abs_i32 s9, s8
	v_cvt_f32_u32_e32 v0, s9
	s_sub_i32 s12, 0, s9
	s_andn2_b32 s2, s2, 63
	s_sub_i32 s10, s4, s2
	v_rcp_iflag_f32_e32 v0, v0
	s_abs_i32 s2, s10
	s_xor_b32 s11, s10, s8
	s_ashr_i32 s11, s11, 31
	v_mul_f32_e32 v0, 0x4f7ffffe, v0
	v_cvt_u32_f32_e32 v0, v0
	v_mov_b32_e32 v181, v179
	v_readfirstlane_b32 s13, v0
	s_mul_i32 s12, s12, s13
	s_mul_hi_u32 s12, s13, s12
	s_add_i32 s13, s13, s12
	s_mul_hi_u32 s12, s2, s13
	s_mul_i32 s13, s12, s9
	s_sub_i32 s2, s2, s13
	s_add_i32 s14, s12, 1
	s_sub_i32 s13, s2, s9
	s_cmp_ge_u32 s2, s9
	s_cselect_b32 s12, s14, s12
	s_cselect_b32 s2, s13, s2
	s_add_i32 s13, s12, 1
	s_cmp_ge_u32 s2, s9
	s_cselect_b32 s2, s13, s12
	s_xor_b32 s2, s2, s11
	s_sub_i32 s2, s2, s11
	s_mul_i32 s8, s8, s2
	s_add_i32 s3, s3, s7
	s_sub_i32 s8, s10, s8
	v_ashrrev_i32_e32 v237, 6, v181
	s_add_i32 s8, s3, s8
	v_lshlrev_b32_e32 v0, 1, v237
	v_lshl_add_u32 v0, s8, 3, v0
	v_ashrrev_i32_e32 v1, 31, v0
	v_bfe_u32 v183, v181, 5, 1
	v_lshlrev_b64 v[0:1], 16, v[0:1]
	v_and_b32_e32 v238, 31, v181
	v_lshl_add_u64 v[0:1], s[64:65], 0, v[0:1]
	v_lshlrev_b32_e32 v176, 9, v183
	s_ashr_i32 s3, s2, 31
	v_lshl_add_u64 v[0:1], v[0:1], 0, v[176:177]
	v_lshlrev_b32_e32 v176, 4, v238
	v_ashrrev_i32_e32 v40, 2, v181
	s_lshl_b64 s[10:11], s[2:3], 18
	v_lshl_add_u64 v[184:185], v[0:1], 0, v[176:177]
	s_add_u32 s10, s5, s10
	v_lshlrev_b32_e32 v0, 5, v40
	s_addc_u32 s11, s6, s11
	v_ashrrev_i32_e32 v1, 31, v0
	v_lshlrev_b32_e32 v2, 4, v181
	v_lshl_add_u64 v[0:1], v[0:1], 1, s[10:11]
	v_and_b32_e32 v176, 48, v2
	v_lshl_add_u64 v[186:187], v[0:1], 0, v[176:177]
	s_movk_i32 s3, 0x2000
	v_add_co_u32_e32 v36, vcc, s3, v186
	v_mul_u32_u24_e32 v38, 40, v238
	s_nop 0
	v_addc_co_u32_e32 v37, vcc, 0, v187, vcc
	v_lshlrev_b32_e32 v39, 4, v183
	v_lshl_add_u32 v240, v38, 1, v39
	v_add_co_u32_e32 v38, vcc, s41, v184
	s_movk_i32 s9, 0x50
	s_nop 0
	v_addc_co_u32_e32 v39, vcc, 0, v185, vcc
	v_and_b32_e32 v239, 63, v181
	s_cmp_eq_u32 s100, 1
	s_cbranch_scc1 .Lhx_out_half
	v_bfe_u32 v247, v181, 4, 2
	v_lshlrev_b32_e32 v247, 1, v247
	v_mov_b32_e32 v176, 0x78
	v_lshrrev_b32_e32 v247, v247, v176
	v_and_b32_e32 v247, 3, v247
	v_and_b32_e32 v246, 3, v181
	v_xor_b32_e32 v247, v247, v246
	v_lshlrev_b32_e32 v247, 4, v247
	v_and_b32_e32 v188, 0xffffffcf, v186
	v_or_b32_e32 v188, v188, v247
	v_mov_b32_e32 v189, v187
	v_lshrrev_b32_e32 v176, 6, v181
	v_lshlrev_b32_e32 v247, 11, v176
	v_lshlrev_b32_e32 v176, 10, v176
	v_lshl_add_u64 v[188:189], v[188:189], 0, v[176:177]
	v_readfirstlane_b32 vcc_lo, v247
	v_bfe_u32 v247, v181, 4, 1
	v_lshlrev_b32_e32 v176, 9, v183
	v_lshl_add_u32 v176, v247, 8, v176
	v_lshl_add_u64 v[184:185], v[184:185], 0, v[176:177]
	v_mov_b32_e32 v176, s41
	v_lshl_add_u64 v[186:187], v[184:185], 0, v[176:177]
	v_mov_b32_e32 v176, 0x78
	v_bfe_u32 v247, v181, 2, 2
	v_lshlrev_b32_e32 v247, 1, v247
	v_lshrrev_b32_e32 v247, v247, v176
	v_and_b32_e32 v247, 3, v247
	v_bfe_u32 v246, v181, 4, 2
	v_xor_b32_e32 v247, v247, v246
	v_lshlrev_b32_e32 v247, 4, v247
	v_and_b32_e32 v246, 15, v181
	v_lshl_add_u32 v246, v246, 6, v247
	s_mov_b32 s96, 0
	s_mov_b32 m0, vcc_lo
	v_lshl_add_u64 v[160:161], v[188:189], 0, s[96:97]
	global_load_lds_dwordx4 v[160:161], off
	global_load_lds_dwordx4 v[160:161], off offset:1024
	s_mov_b32 s96, 0
	v_lshl_add_u64 v[248:249], v[184:185], 0, s[96:97]
	v_lshl_add_u64 v[250:251], v[186:187], 0, s[96:97]
	global_load_dwordx4 v[128:131], v[248:249], off
	global_load_dwordx4 v[132:135], v[248:249], off offset:256
	global_load_dwordx4 v[136:139], v[250:251], off
	global_load_dwordx4 v[140:143], v[250:251], off offset:256
	s_movk_i32 s96, 0x2000
	s_add_i32 m0, vcc_lo, 8192
	v_lshl_add_u64 v[160:161], v[188:189], 0, s[96:97]
	global_load_lds_dwordx4 v[160:161], off
	global_load_lds_dwordx4 v[160:161], off offset:1024
	s_movk_i32 s96, 0x800
	v_lshl_add_u64 v[248:249], v[184:185], 0, s[96:97]
	v_lshl_add_u64 v[250:251], v[186:187], 0, s[96:97]
	global_load_dwordx4 v[144:147], v[248:249], off
	global_load_dwordx4 v[148:151], v[248:249], off offset:256
	global_load_dwordx4 v[152:155], v[250:251], off
	global_load_dwordx4 v[156:159], v[250:251], off offset:256
	v_mov_b32_e32 v0, 0
	v_mov_b32_e32 v1, 0
	v_mov_b32_e32 v2, 0
	v_mov_b32_e32 v3, 0
	v_mov_b32_e32 v4, 0
	v_mov_b32_e32 v5, 0
	v_mov_b32_e32 v6, 0
	v_mov_b32_e32 v7, 0
	v_mov_b32_e32 v8, 0
	v_mov_b32_e32 v9, 0
	v_mov_b32_e32 v10, 0
	v_mov_b32_e32 v11, 0
	v_mov_b32_e32 v12, 0
	v_mov_b32_e32 v13, 0
	v_mov_b32_e32 v14, 0
	v_mov_b32_e32 v15, 0
	v_mov_b32_e32 v16, 0
	v_mov_b32_e32 v17, 0
	v_mov_b32_e32 v18, 0
	v_mov_b32_e32 v19, 0
	v_mov_b32_e32 v20, 0
	v_mov_b32_e32 v21, 0
	v_mov_b32_e32 v22, 0
	v_mov_b32_e32 v23, 0
	v_mov_b32_e32 v24, 0
	v_mov_b32_e32 v25, 0
	v_mov_b32_e32 v26, 0
	v_mov_b32_e32 v27, 0
	v_mov_b32_e32 v28, 0
	v_mov_b32_e32 v29, 0
	v_mov_b32_e32 v30, 0
	v_mov_b32_e32 v31, 0
	v_mov_b32_e32 v32, 0
	v_mov_b32_e32 v33, 0
	v_mov_b32_e32 v34, 0
	v_mov_b32_e32 v35, 0
	v_mov_b32_e32 v36, 0
	v_mov_b32_e32 v37, 0
	v_mov_b32_e32 v38, 0
	v_mov_b32_e32 v39, 0
	v_mov_b32_e32 v40, 0
	v_mov_b32_e32 v41, 0
	v_mov_b32_e32 v42, 0
	v_mov_b32_e32 v43, 0
	v_mov_b32_e32 v44, 0
	v_mov_b32_e32 v45, 0
	v_mov_b32_e32 v46, 0
	v_mov_b32_e32 v47, 0
	v_mov_b32_e32 v48, 0
	v_mov_b32_e32 v49, 0
	v_mov_b32_e32 v50, 0
	v_mov_b32_e32 v51, 0
	v_mov_b32_e32 v52, 0
	v_mov_b32_e32 v53, 0
	v_mov_b32_e32 v54, 0
	v_mov_b32_e32 v55, 0
	v_mov_b32_e32 v56, 0
	v_mov_b32_e32 v57, 0
	v_mov_b32_e32 v58, 0
	v_mov_b32_e32 v59, 0
	v_mov_b32_e32 v60, 0
	v_mov_b32_e32 v61, 0
	v_mov_b32_e32 v62, 0
	v_mov_b32_e32 v63, 0
	v_mov_b32_e32 v64, 0
	v_mov_b32_e32 v65, 0
	v_mov_b32_e32 v66, 0
	v_mov_b32_e32 v67, 0
	v_mov_b32_e32 v68, 0
	v_mov_b32_e32 v69, 0
	v_mov_b32_e32 v70, 0
	v_mov_b32_e32 v71, 0
	v_mov_b32_e32 v72, 0
	v_mov_b32_e32 v73, 0
	v_mov_b32_e32 v74, 0
	v_mov_b32_e32 v75, 0
	v_mov_b32_e32 v76, 0
	v_mov_b32_e32 v77, 0
	v_mov_b32_e32 v78, 0
	v_mov_b32_e32 v79, 0
	v_mov_b32_e32 v80, 0
	v_mov_b32_e32 v81, 0
	v_mov_b32_e32 v82, 0
	v_mov_b32_e32 v83, 0
	v_mov_b32_e32 v84, 0
	v_mov_b32_e32 v85, 0
	v_mov_b32_e32 v86, 0
	v_mov_b32_e32 v87, 0
	v_mov_b32_e32 v88, 0
	v_mov_b32_e32 v89, 0
	v_mov_b32_e32 v90, 0
	v_mov_b32_e32 v91, 0
	v_mov_b32_e32 v92, 0
	v_mov_b32_e32 v93, 0
	v_mov_b32_e32 v94, 0
	v_mov_b32_e32 v95, 0
	v_mov_b32_e32 v96, 0
	v_mov_b32_e32 v97, 0
	v_mov_b32_e32 v98, 0
	v_mov_b32_e32 v99, 0
	v_mov_b32_e32 v100, 0
	v_mov_b32_e32 v101, 0
	v_mov_b32_e32 v102, 0
	v_mov_b32_e32 v103, 0
	v_mov_b32_e32 v104, 0
	v_mov_b32_e32 v105, 0
	v_mov_b32_e32 v106, 0
	v_mov_b32_e32 v107, 0
	v_mov_b32_e32 v108, 0
	v_mov_b32_e32 v109, 0
	v_mov_b32_e32 v110, 0
	v_mov_b32_e32 v111, 0
	v_mov_b32_e32 v112, 0
	v_mov_b32_e32 v113, 0
	v_mov_b32_e32 v114, 0
	v_mov_b32_e32 v115, 0
	v_mov_b32_e32 v116, 0
	v_mov_b32_e32 v117, 0
	v_mov_b32_e32 v118, 0
	v_mov_b32_e32 v119, 0
	v_mov_b32_e32 v120, 0
	v_mov_b32_e32 v121, 0
	v_mov_b32_e32 v122, 0
	v_mov_b32_e32 v123, 0
	v_mov_b32_e32 v124, 0
	v_mov_b32_e32 v125, 0
	v_mov_b32_e32 v126, 0
	v_mov_b32_e32 v127, 0
	s_mov_b32 s3, 0
	s_waitcnt vmcnt(4)
	s_barrier
.Lg16_out_k:
	s_add_i32 s9, s3, 2
	s_lshl_b32 s96, s9, 13
	s_add_i32 m0, vcc_lo, 16384
	v_lshl_add_u64 v[160:161], v[188:189], 0, s[96:97]
	global_load_lds_dwordx4 v[160:161], off
	global_load_lds_dwordx4 v[160:161], off offset:1024
	ds_read_b128 v[196:199], v246 offset:0
	ds_read_b128 v[200:203], v246 offset:1024
	ds_read_b128 v[204:207], v246 offset:2048
	ds_read_b128 v[242:245], v246 offset:3072
	s_add_i32 s9, s3, 2
	s_lshl_b32 s96, s9, 11
	v_lshl_add_u64 v[248:249], v[184:185], 0, s[96:97]
	v_lshl_add_u64 v[250:251], v[186:187], 0, s[96:97]
	s_waitcnt vmcnt(8) lgkmcnt(3)
	v_mfma_f32_16x16x32_bf16 v[112:115], v[128:131], v[196:199], v[112:115]
	v_mfma_f32_16x16x32_bf16 v[120:123], v[132:135], v[196:199], v[120:123]
	v_mfma_f32_16x16x32_bf16 v[48:51], v[136:139], v[196:199], v[48:51]
	v_mfma_f32_16x16x32_bf16 v[56:59], v[140:143], v[196:199], v[56:59]
	ds_read_b128 v[196:199], v246 offset:4096
	s_waitcnt lgkmcnt(3)
	v_mfma_f32_16x16x32_bf16 v[116:119], v[128:131], v[200:203], v[116:119]
	v_mfma_f32_16x16x32_bf16 v[124:127], v[132:135], v[200:203], v[124:127]
	v_mfma_f32_16x16x32_bf16 v[52:55], v[136:139], v[200:203], v[52:55]
	v_mfma_f32_16x16x32_bf16 v[60:63], v[140:143], v[200:203], v[60:63]
	ds_read_b128 v[200:203], v246 offset:5120
	s_waitcnt lgkmcnt(3)
	v_mfma_f32_16x16x32_bf16 v[96:99], v[128:131], v[204:207], v[96:99]
	v_mfma_f32_16x16x32_bf16 v[104:107], v[132:135], v[204:207], v[104:107]
	v_mfma_f32_16x16x32_bf16 v[32:35], v[136:139], v[204:207], v[32:35]
	v_mfma_f32_16x16x32_bf16 v[40:43], v[140:143], v[204:207], v[40:43]
	ds_read_b128 v[204:207], v246 offset:6144
	s_waitcnt lgkmcnt(3)
	v_mfma_f32_16x16x32_bf16 v[100:103], v[128:131], v[242:245], v[100:103]
	v_mfma_f32_16x16x32_bf16 v[108:111], v[132:135], v[242:245], v[108:111]
	v_mfma_f32_16x16x32_bf16 v[36:39], v[136:139], v[242:245], v[36:39]
	v_mfma_f32_16x16x32_bf16 v[44:47], v[140:143], v[242:245], v[44:47]
	ds_read_b128 v[242:245], v246 offset:7168
	s_waitcnt lgkmcnt(3)
	v_mfma_f32_16x16x32_bf16 v[80:83], v[128:131], v[196:199], v[80:83]
	v_mfma_f32_16x16x32_bf16 v[88:91], v[132:135], v[196:199], v[88:91]
	v_mfma_f32_16x16x32_bf16 v[16:19], v[136:139], v[196:199], v[16:19]
	v_mfma_f32_16x16x32_bf16 v[24:27], v[140:143], v[196:199], v[24:27]
	s_waitcnt lgkmcnt(2)
	v_mfma_f32_16x16x32_bf16 v[84:87], v[128:131], v[200:203], v[84:87]
	v_mfma_f32_16x16x32_bf16 v[92:95], v[132:135], v[200:203], v[92:95]
	v_mfma_f32_16x16x32_bf16 v[20:23], v[136:139], v[200:203], v[20:23]
	v_mfma_f32_16x16x32_bf16 v[28:31], v[140:143], v[200:203], v[28:31]
	s_waitcnt lgkmcnt(1)
	v_mfma_f32_16x16x32_bf16 v[64:67], v[128:131], v[204:207], v[64:67]
	v_mfma_f32_16x16x32_bf16 v[72:75], v[132:135], v[204:207], v[72:75]
	v_mfma_f32_16x16x32_bf16 v[0:3], v[136:139], v[204:207], v[0:3]
	v_mfma_f32_16x16x32_bf16 v[8:11], v[140:143], v[204:207], v[8:11]
	s_waitcnt lgkmcnt(0)
	v_mfma_f32_16x16x32_bf16 v[68:71], v[128:131], v[242:245], v[68:71]
	v_mfma_f32_16x16x32_bf16 v[76:79], v[132:135], v[242:245], v[76:79]
	v_mfma_f32_16x16x32_bf16 v[4:7], v[136:139], v[242:245], v[4:7]
	v_mfma_f32_16x16x32_bf16 v[12:15], v[140:143], v[242:245], v[12:15]
	global_load_dwordx4 v[128:131], v[248:249], off
	global_load_dwordx4 v[132:135], v[248:249], off offset:256
	global_load_dwordx4 v[136:139], v[250:251], off
	global_load_dwordx4 v[140:143], v[250:251], off offset:256
	s_waitcnt vmcnt(10)
	s_barrier
	s_add_i32 s9, s3, 3
	s_lshl_b32 s96, s9, 13
	s_mov_b32 m0, vcc_lo
	v_lshl_add_u64 v[160:161], v[188:189], 0, s[96:97]
	global_load_lds_dwordx4 v[160:161], off
	global_load_lds_dwordx4 v[160:161], off offset:1024
	ds_read_b128 v[196:199], v246 offset:8192
	ds_read_b128 v[200:203], v246 offset:9216
	ds_read_b128 v[204:207], v246 offset:10240
	ds_read_b128 v[242:245], v246 offset:11264
	s_add_i32 s9, s3, 3
	s_lshl_b32 s96, s9, 11
	v_lshl_add_u64 v[248:249], v[184:185], 0, s[96:97]
	v_lshl_add_u64 v[250:251], v[186:187], 0, s[96:97]
	s_waitcnt vmcnt(8) lgkmcnt(3)
	v_mfma_f32_16x16x32_bf16 v[112:115], v[144:147], v[196:199], v[112:115]
	v_mfma_f32_16x16x32_bf16 v[120:123], v[148:151], v[196:199], v[120:123]
	v_mfma_f32_16x16x32_bf16 v[48:51], v[152:155], v[196:199], v[48:51]
	v_mfma_f32_16x16x32_bf16 v[56:59], v[156:159], v[196:199], v[56:59]
	ds_read_b128 v[196:199], v246 offset:12288
	s_waitcnt lgkmcnt(3)
	v_mfma_f32_16x16x32_bf16 v[116:119], v[144:147], v[200:203], v[116:119]
	v_mfma_f32_16x16x32_bf16 v[124:127], v[148:151], v[200:203], v[124:127]
	v_mfma_f32_16x16x32_bf16 v[52:55], v[152:155], v[200:203], v[52:55]
	v_mfma_f32_16x16x32_bf16 v[60:63], v[156:159], v[200:203], v[60:63]
	ds_read_b128 v[200:203], v246 offset:13312
	s_waitcnt lgkmcnt(3)
	v_mfma_f32_16x16x32_bf16 v[96:99], v[144:147], v[204:207], v[96:99]
	v_mfma_f32_16x16x32_bf16 v[104:107], v[148:151], v[204:207], v[104:107]
	v_mfma_f32_16x16x32_bf16 v[32:35], v[152:155], v[204:207], v[32:35]
	v_mfma_f32_16x16x32_bf16 v[40:43], v[156:159], v[204:207], v[40:43]
	ds_read_b128 v[204:207], v246 offset:14336
	s_waitcnt lgkmcnt(3)
	v_mfma_f32_16x16x32_bf16 v[100:103], v[144:147], v[242:245], v[100:103]
	v_mfma_f32_16x16x32_bf16 v[108:111], v[148:151], v[242:245], v[108:111]
	v_mfma_f32_16x16x32_bf16 v[36:39], v[152:155], v[242:245], v[36:39]
	v_mfma_f32_16x16x32_bf16 v[44:47], v[156:159], v[242:245], v[44:47]
	ds_read_b128 v[242:245], v246 offset:15360
	s_waitcnt lgkmcnt(3)
	v_mfma_f32_16x16x32_bf16 v[80:83], v[144:147], v[196:199], v[80:83]
	v_mfma_f32_16x16x32_bf16 v[88:91], v[148:151], v[196:199], v[88:91]
	v_mfma_f32_16x16x32_bf16 v[16:19], v[152:155], v[196:199], v[16:19]
	v_mfma_f32_16x16x32_bf16 v[24:27], v[156:159], v[196:199], v[24:27]
	s_waitcnt lgkmcnt(2)
	v_mfma_f32_16x16x32_bf16 v[84:87], v[144:147], v[200:203], v[84:87]
	v_mfma_f32_16x16x32_bf16 v[92:95], v[148:151], v[200:203], v[92:95]
	v_mfma_f32_16x16x32_bf16 v[20:23], v[152:155], v[200:203], v[20:23]
	v_mfma_f32_16x16x32_bf16 v[28:31], v[156:159], v[200:203], v[28:31]
	s_waitcnt lgkmcnt(1)
	v_mfma_f32_16x16x32_bf16 v[64:67], v[144:147], v[204:207], v[64:67]
	v_mfma_f32_16x16x32_bf16 v[72:75], v[148:151], v[204:207], v[72:75]
	v_mfma_f32_16x16x32_bf16 v[0:3], v[152:155], v[204:207], v[0:3]
	v_mfma_f32_16x16x32_bf16 v[8:11], v[156:159], v[204:207], v[8:11]
	s_waitcnt lgkmcnt(0)
	v_mfma_f32_16x16x32_bf16 v[68:71], v[144:147], v[242:245], v[68:71]
	v_mfma_f32_16x16x32_bf16 v[76:79], v[148:151], v[242:245], v[76:79]
	v_mfma_f32_16x16x32_bf16 v[4:7], v[152:155], v[242:245], v[4:7]
	v_mfma_f32_16x16x32_bf16 v[12:15], v[156:159], v[242:245], v[12:15]
	global_load_dwordx4 v[144:147], v[248:249], off
	global_load_dwordx4 v[148:151], v[248:249], off offset:256
	global_load_dwordx4 v[152:155], v[250:251], off
	global_load_dwordx4 v[156:159], v[250:251], off offset:256
	s_waitcnt vmcnt(10)
	s_barrier
	s_add_i32 s9, s3, 4
	s_lshl_b32 s96, s9, 13
	s_add_i32 m0, vcc_lo, 8192
	v_lshl_add_u64 v[160:161], v[188:189], 0, s[96:97]
	global_load_lds_dwordx4 v[160:161], off
	global_load_lds_dwordx4 v[160:161], off offset:1024
	ds_read_b128 v[196:199], v246 offset:16384
	ds_read_b128 v[200:203], v246 offset:17408
	ds_read_b128 v[204:207], v246 offset:18432
	ds_read_b128 v[242:245], v246 offset:19456
	s_add_i32 s9, s3, 4
	s_lshl_b32 s96, s9, 11
	v_lshl_add_u64 v[248:249], v[184:185], 0, s[96:97]
	v_lshl_add_u64 v[250:251], v[186:187], 0, s[96:97]
	s_waitcnt vmcnt(8) lgkmcnt(3)
	v_mfma_f32_16x16x32_bf16 v[112:115], v[128:131], v[196:199], v[112:115]
	v_mfma_f32_16x16x32_bf16 v[120:123], v[132:135], v[196:199], v[120:123]
	v_mfma_f32_16x16x32_bf16 v[48:51], v[136:139], v[196:199], v[48:51]
	v_mfma_f32_16x16x32_bf16 v[56:59], v[140:143], v[196:199], v[56:59]
	ds_read_b128 v[196:199], v246 offset:20480
	s_waitcnt lgkmcnt(3)
	v_mfma_f32_16x16x32_bf16 v[116:119], v[128:131], v[200:203], v[116:119]
	v_mfma_f32_16x16x32_bf16 v[124:127], v[132:135], v[200:203], v[124:127]
	v_mfma_f32_16x16x32_bf16 v[52:55], v[136:139], v[200:203], v[52:55]
	v_mfma_f32_16x16x32_bf16 v[60:63], v[140:143], v[200:203], v[60:63]
	ds_read_b128 v[200:203], v246 offset:21504
	s_waitcnt lgkmcnt(3)
	v_mfma_f32_16x16x32_bf16 v[96:99], v[128:131], v[204:207], v[96:99]
	v_mfma_f32_16x16x32_bf16 v[104:107], v[132:135], v[204:207], v[104:107]
	v_mfma_f32_16x16x32_bf16 v[32:35], v[136:139], v[204:207], v[32:35]
	v_mfma_f32_16x16x32_bf16 v[40:43], v[140:143], v[204:207], v[40:43]
	ds_read_b128 v[204:207], v246 offset:22528
	s_waitcnt lgkmcnt(3)
	v_mfma_f32_16x16x32_bf16 v[100:103], v[128:131], v[242:245], v[100:103]
	v_mfma_f32_16x16x32_bf16 v[108:111], v[132:135], v[242:245], v[108:111]
	v_mfma_f32_16x16x32_bf16 v[36:39], v[136:139], v[242:245], v[36:39]
	v_mfma_f32_16x16x32_bf16 v[44:47], v[140:143], v[242:245], v[44:47]
	ds_read_b128 v[242:245], v246 offset:23552
	s_waitcnt lgkmcnt(3)
	v_mfma_f32_16x16x32_bf16 v[80:83], v[128:131], v[196:199], v[80:83]
	v_mfma_f32_16x16x32_bf16 v[88:91], v[132:135], v[196:199], v[88:91]
	v_mfma_f32_16x16x32_bf16 v[16:19], v[136:139], v[196:199], v[16:19]
	v_mfma_f32_16x16x32_bf16 v[24:27], v[140:143], v[196:199], v[24:27]
	s_waitcnt lgkmcnt(2)
	v_mfma_f32_16x16x32_bf16 v[84:87], v[128:131], v[200:203], v[84:87]
	v_mfma_f32_16x16x32_bf16 v[92:95], v[132:135], v[200:203], v[92:95]
	v_mfma_f32_16x16x32_bf16 v[20:23], v[136:139], v[200:203], v[20:23]
	v_mfma_f32_16x16x32_bf16 v[28:31], v[140:143], v[200:203], v[28:31]
	s_waitcnt lgkmcnt(1)
	v_mfma_f32_16x16x32_bf16 v[64:67], v[128:131], v[204:207], v[64:67]
	v_mfma_f32_16x16x32_bf16 v[72:75], v[132:135], v[204:207], v[72:75]
	v_mfma_f32_16x16x32_bf16 v[0:3], v[136:139], v[204:207], v[0:3]
	v_mfma_f32_16x16x32_bf16 v[8:11], v[140:143], v[204:207], v[8:11]
	s_waitcnt lgkmcnt(0)
	v_mfma_f32_16x16x32_bf16 v[68:71], v[128:131], v[242:245], v[68:71]
	v_mfma_f32_16x16x32_bf16 v[76:79], v[132:135], v[242:245], v[76:79]
	v_mfma_f32_16x16x32_bf16 v[4:7], v[136:139], v[242:245], v[4:7]
	v_mfma_f32_16x16x32_bf16 v[12:15], v[140:143], v[242:245], v[12:15]
	global_load_dwordx4 v[128:131], v[248:249], off
	global_load_dwordx4 v[132:135], v[248:249], off offset:256
	global_load_dwordx4 v[136:139], v[250:251], off
	global_load_dwordx4 v[140:143], v[250:251], off offset:256
	s_waitcnt vmcnt(10)
	s_barrier
	s_add_i32 s9, s3, 5
	s_lshl_b32 s96, s9, 13
	s_add_i32 m0, vcc_lo, 16384
	v_lshl_add_u64 v[160:161], v[188:189], 0, s[96:97]
	global_load_lds_dwordx4 v[160:161], off
	global_load_lds_dwordx4 v[160:161], off offset:1024
	ds_read_b128 v[196:199], v246 offset:0
	ds_read_b128 v[200:203], v246 offset:1024
	ds_read_b128 v[204:207], v246 offset:2048
	ds_read_b128 v[242:245], v246 offset:3072
	s_add_i32 s9, s3, 5
	s_lshl_b32 s96, s9, 11
	v_lshl_add_u64 v[248:249], v[184:185], 0, s[96:97]
	v_lshl_add_u64 v[250:251], v[186:187], 0, s[96:97]
	s_waitcnt vmcnt(8) lgkmcnt(3)
	v_mfma_f32_16x16x32_bf16 v[112:115], v[144:147], v[196:199], v[112:115]
	v_mfma_f32_16x16x32_bf16 v[120:123], v[148:151], v[196:199], v[120:123]
	v_mfma_f32_16x16x32_bf16 v[48:51], v[152:155], v[196:199], v[48:51]
	v_mfma_f32_16x16x32_bf16 v[56:59], v[156:159], v[196:199], v[56:59]
	ds_read_b128 v[196:199], v246 offset:4096
	s_waitcnt lgkmcnt(3)
	v_mfma_f32_16x16x32_bf16 v[116:119], v[144:147], v[200:203], v[116:119]
	v_mfma_f32_16x16x32_bf16 v[124:127], v[148:151], v[200:203], v[124:127]
	v_mfma_f32_16x16x32_bf16 v[52:55], v[152:155], v[200:203], v[52:55]
	v_mfma_f32_16x16x32_bf16 v[60:63], v[156:159], v[200:203], v[60:63]
	ds_read_b128 v[200:203], v246 offset:5120
	s_waitcnt lgkmcnt(3)
	v_mfma_f32_16x16x32_bf16 v[96:99], v[144:147], v[204:207], v[96:99]
	v_mfma_f32_16x16x32_bf16 v[104:107], v[148:151], v[204:207], v[104:107]
	v_mfma_f32_16x16x32_bf16 v[32:35], v[152:155], v[204:207], v[32:35]
	v_mfma_f32_16x16x32_bf16 v[40:43], v[156:159], v[204:207], v[40:43]
	ds_read_b128 v[204:207], v246 offset:6144
	s_waitcnt lgkmcnt(3)
	v_mfma_f32_16x16x32_bf16 v[100:103], v[144:147], v[242:245], v[100:103]
	v_mfma_f32_16x16x32_bf16 v[108:111], v[148:151], v[242:245], v[108:111]
	v_mfma_f32_16x16x32_bf16 v[36:39], v[152:155], v[242:245], v[36:39]
	v_mfma_f32_16x16x32_bf16 v[44:47], v[156:159], v[242:245], v[44:47]
	ds_read_b128 v[242:245], v246 offset:7168
	s_waitcnt lgkmcnt(3)
	v_mfma_f32_16x16x32_bf16 v[80:83], v[144:147], v[196:199], v[80:83]
	v_mfma_f32_16x16x32_bf16 v[88:91], v[148:151], v[196:199], v[88:91]
	v_mfma_f32_16x16x32_bf16 v[16:19], v[152:155], v[196:199], v[16:19]
	v_mfma_f32_16x16x32_bf16 v[24:27], v[156:159], v[196:199], v[24:27]
	s_waitcnt lgkmcnt(2)
	v_mfma_f32_16x16x32_bf16 v[84:87], v[144:147], v[200:203], v[84:87]
	v_mfma_f32_16x16x32_bf16 v[92:95], v[148:151], v[200:203], v[92:95]
	v_mfma_f32_16x16x32_bf16 v[20:23], v[152:155], v[200:203], v[20:23]
	v_mfma_f32_16x16x32_bf16 v[28:31], v[156:159], v[200:203], v[28:31]
	s_waitcnt lgkmcnt(1)
	v_mfma_f32_16x16x32_bf16 v[64:67], v[144:147], v[204:207], v[64:67]
	v_mfma_f32_16x16x32_bf16 v[72:75], v[148:151], v[204:207], v[72:75]
	v_mfma_f32_16x16x32_bf16 v[0:3], v[152:155], v[204:207], v[0:3]
	v_mfma_f32_16x16x32_bf16 v[8:11], v[156:159], v[204:207], v[8:11]
	s_waitcnt lgkmcnt(0)
	v_mfma_f32_16x16x32_bf16 v[68:71], v[144:147], v[242:245], v[68:71]
	v_mfma_f32_16x16x32_bf16 v[76:79], v[148:151], v[242:245], v[76:79]
	v_mfma_f32_16x16x32_bf16 v[4:7], v[152:155], v[242:245], v[4:7]
	v_mfma_f32_16x16x32_bf16 v[12:15], v[156:159], v[242:245], v[12:15]
	global_load_dwordx4 v[144:147], v[248:249], off
	global_load_dwordx4 v[148:151], v[248:249], off offset:256
	global_load_dwordx4 v[152:155], v[250:251], off
	global_load_dwordx4 v[156:159], v[250:251], off offset:256
	s_waitcnt vmcnt(10)
	s_barrier
	s_add_i32 s9, s3, 6
	s_lshl_b32 s96, s9, 13
	s_mov_b32 m0, vcc_lo
	v_lshl_add_u64 v[160:161], v[188:189], 0, s[96:97]
	global_load_lds_dwordx4 v[160:161], off
	global_load_lds_dwordx4 v[160:161], off offset:1024
	ds_read_b128 v[196:199], v246 offset:8192
	ds_read_b128 v[200:203], v246 offset:9216
	ds_read_b128 v[204:207], v246 offset:10240
	ds_read_b128 v[242:245], v246 offset:11264
	s_add_i32 s9, s3, 6
	s_lshl_b32 s96, s9, 11
	v_lshl_add_u64 v[248:249], v[184:185], 0, s[96:97]
	v_lshl_add_u64 v[250:251], v[186:187], 0, s[96:97]
	s_waitcnt vmcnt(8) lgkmcnt(3)
	v_mfma_f32_16x16x32_bf16 v[112:115], v[128:131], v[196:199], v[112:115]
	v_mfma_f32_16x16x32_bf16 v[120:123], v[132:135], v[196:199], v[120:123]
	v_mfma_f32_16x16x32_bf16 v[48:51], v[136:139], v[196:199], v[48:51]
	v_mfma_f32_16x16x32_bf16 v[56:59], v[140:143], v[196:199], v[56:59]
	ds_read_b128 v[196:199], v246 offset:12288
	s_waitcnt lgkmcnt(3)
	v_mfma_f32_16x16x32_bf16 v[116:119], v[128:131], v[200:203], v[116:119]
	v_mfma_f32_16x16x32_bf16 v[124:127], v[132:135], v[200:203], v[124:127]
	v_mfma_f32_16x16x32_bf16 v[52:55], v[136:139], v[200:203], v[52:55]
	v_mfma_f32_16x16x32_bf16 v[60:63], v[140:143], v[200:203], v[60:63]
	ds_read_b128 v[200:203], v246 offset:13312
	s_waitcnt lgkmcnt(3)
	v_mfma_f32_16x16x32_bf16 v[96:99], v[128:131], v[204:207], v[96:99]
	v_mfma_f32_16x16x32_bf16 v[104:107], v[132:135], v[204:207], v[104:107]
	v_mfma_f32_16x16x32_bf16 v[32:35], v[136:139], v[204:207], v[32:35]
	v_mfma_f32_16x16x32_bf16 v[40:43], v[140:143], v[204:207], v[40:43]
	ds_read_b128 v[204:207], v246 offset:14336
	s_waitcnt lgkmcnt(3)
	v_mfma_f32_16x16x32_bf16 v[100:103], v[128:131], v[242:245], v[100:103]
	v_mfma_f32_16x16x32_bf16 v[108:111], v[132:135], v[242:245], v[108:111]
	v_mfma_f32_16x16x32_bf16 v[36:39], v[136:139], v[242:245], v[36:39]
	v_mfma_f32_16x16x32_bf16 v[44:47], v[140:143], v[242:245], v[44:47]
	ds_read_b128 v[242:245], v246 offset:15360
	s_waitcnt lgkmcnt(3)
	v_mfma_f32_16x16x32_bf16 v[80:83], v[128:131], v[196:199], v[80:83]
	v_mfma_f32_16x16x32_bf16 v[88:91], v[132:135], v[196:199], v[88:91]
	v_mfma_f32_16x16x32_bf16 v[16:19], v[136:139], v[196:199], v[16:19]
	v_mfma_f32_16x16x32_bf16 v[24:27], v[140:143], v[196:199], v[24:27]
	s_waitcnt lgkmcnt(2)
	v_mfma_f32_16x16x32_bf16 v[84:87], v[128:131], v[200:203], v[84:87]
	v_mfma_f32_16x16x32_bf16 v[92:95], v[132:135], v[200:203], v[92:95]
	v_mfma_f32_16x16x32_bf16 v[20:23], v[136:139], v[200:203], v[20:23]
	v_mfma_f32_16x16x32_bf16 v[28:31], v[140:143], v[200:203], v[28:31]
	s_waitcnt lgkmcnt(1)
	v_mfma_f32_16x16x32_bf16 v[64:67], v[128:131], v[204:207], v[64:67]
	v_mfma_f32_16x16x32_bf16 v[72:75], v[132:135], v[204:207], v[72:75]
	v_mfma_f32_16x16x32_bf16 v[0:3], v[136:139], v[204:207], v[0:3]
	v_mfma_f32_16x16x32_bf16 v[8:11], v[140:143], v[204:207], v[8:11]
	s_waitcnt lgkmcnt(0)
	v_mfma_f32_16x16x32_bf16 v[68:71], v[128:131], v[242:245], v[68:71]
	v_mfma_f32_16x16x32_bf16 v[76:79], v[132:135], v[242:245], v[76:79]
	v_mfma_f32_16x16x32_bf16 v[4:7], v[136:139], v[242:245], v[4:7]
	v_mfma_f32_16x16x32_bf16 v[12:15], v[140:143], v[242:245], v[12:15]
	global_load_dwordx4 v[128:131], v[248:249], off
	global_load_dwordx4 v[132:135], v[248:249], off offset:256
	global_load_dwordx4 v[136:139], v[250:251], off
	global_load_dwordx4 v[140:143], v[250:251], off offset:256
	s_waitcnt vmcnt(10)
	s_barrier
	s_add_i32 s9, s3, 7
	s_lshl_b32 s96, s9, 13
	s_add_i32 m0, vcc_lo, 8192
	v_lshl_add_u64 v[160:161], v[188:189], 0, s[96:97]
	global_load_lds_dwordx4 v[160:161], off
	global_load_lds_dwordx4 v[160:161], off offset:1024
	ds_read_b128 v[196:199], v246 offset:16384
	ds_read_b128 v[200:203], v246 offset:17408
	ds_read_b128 v[204:207], v246 offset:18432
	ds_read_b128 v[242:245], v246 offset:19456
	s_add_i32 s9, s3, 7
	s_lshl_b32 s96, s9, 11
	v_lshl_add_u64 v[248:249], v[184:185], 0, s[96:97]
	v_lshl_add_u64 v[250:251], v[186:187], 0, s[96:97]
	s_waitcnt vmcnt(8) lgkmcnt(3)
	v_mfma_f32_16x16x32_bf16 v[112:115], v[144:147], v[196:199], v[112:115]
	v_mfma_f32_16x16x32_bf16 v[120:123], v[148:151], v[196:199], v[120:123]
	v_mfma_f32_16x16x32_bf16 v[48:51], v[152:155], v[196:199], v[48:51]
	v_mfma_f32_16x16x32_bf16 v[56:59], v[156:159], v[196:199], v[56:59]
	ds_read_b128 v[196:199], v246 offset:20480
	s_waitcnt lgkmcnt(3)
	v_mfma_f32_16x16x32_bf16 v[116:119], v[144:147], v[200:203], v[116:119]
	v_mfma_f32_16x16x32_bf16 v[124:127], v[148:151], v[200:203], v[124:127]
	v_mfma_f32_16x16x32_bf16 v[52:55], v[152:155], v[200:203], v[52:55]
	v_mfma_f32_16x16x32_bf16 v[60:63], v[156:159], v[200:203], v[60:63]
	ds_read_b128 v[200:203], v246 offset:21504
	s_waitcnt lgkmcnt(3)
	v_mfma_f32_16x16x32_bf16 v[96:99], v[144:147], v[204:207], v[96:99]
	v_mfma_f32_16x16x32_bf16 v[104:107], v[148:151], v[204:207], v[104:107]
	v_mfma_f32_16x16x32_bf16 v[32:35], v[152:155], v[204:207], v[32:35]
	v_mfma_f32_16x16x32_bf16 v[40:43], v[156:159], v[204:207], v[40:43]
	ds_read_b128 v[204:207], v246 offset:22528
	s_waitcnt lgkmcnt(3)
	v_mfma_f32_16x16x32_bf16 v[100:103], v[144:147], v[242:245], v[100:103]
	v_mfma_f32_16x16x32_bf16 v[108:111], v[148:151], v[242:245], v[108:111]
	v_mfma_f32_16x16x32_bf16 v[36:39], v[152:155], v[242:245], v[36:39]
	v_mfma_f32_16x16x32_bf16 v[44:47], v[156:159], v[242:245], v[44:47]
	ds_read_b128 v[242:245], v246 offset:23552
	s_waitcnt lgkmcnt(3)
	v_mfma_f32_16x16x32_bf16 v[80:83], v[144:147], v[196:199], v[80:83]
	v_mfma_f32_16x16x32_bf16 v[88:91], v[148:151], v[196:199], v[88:91]
	v_mfma_f32_16x16x32_bf16 v[16:19], v[152:155], v[196:199], v[16:19]
	v_mfma_f32_16x16x32_bf16 v[24:27], v[156:159], v[196:199], v[24:27]
	s_waitcnt lgkmcnt(2)
	v_mfma_f32_16x16x32_bf16 v[84:87], v[144:147], v[200:203], v[84:87]
	v_mfma_f32_16x16x32_bf16 v[92:95], v[148:151], v[200:203], v[92:95]
	v_mfma_f32_16x16x32_bf16 v[20:23], v[152:155], v[200:203], v[20:23]
	v_mfma_f32_16x16x32_bf16 v[28:31], v[156:159], v[200:203], v[28:31]
	s_waitcnt lgkmcnt(1)
	v_mfma_f32_16x16x32_bf16 v[64:67], v[144:147], v[204:207], v[64:67]
	v_mfma_f32_16x16x32_bf16 v[72:75], v[148:151], v[204:207], v[72:75]
	v_mfma_f32_16x16x32_bf16 v[0:3], v[152:155], v[204:207], v[0:3]
	v_mfma_f32_16x16x32_bf16 v[8:11], v[156:159], v[204:207], v[8:11]
	s_waitcnt lgkmcnt(0)
	v_mfma_f32_16x16x32_bf16 v[68:71], v[144:147], v[242:245], v[68:71]
	v_mfma_f32_16x16x32_bf16 v[76:79], v[148:151], v[242:245], v[76:79]
	v_mfma_f32_16x16x32_bf16 v[4:7], v[152:155], v[242:245], v[4:7]
	v_mfma_f32_16x16x32_bf16 v[12:15], v[156:159], v[242:245], v[12:15]
	global_load_dwordx4 v[144:147], v[248:249], off
	global_load_dwordx4 v[148:151], v[248:249], off offset:256
	global_load_dwordx4 v[152:155], v[250:251], off
	global_load_dwordx4 v[156:159], v[250:251], off offset:256
	s_waitcnt vmcnt(10)
	s_barrier
	s_add_i32 s3, s3, 6
	s_cmp_lt_u32 s3, 30
	s_cbranch_scc1 .Lg16_out_k
	ds_read_b128 v[196:199], v246 offset:0
	ds_read_b128 v[200:203], v246 offset:1024
	ds_read_b128 v[204:207], v246 offset:2048
	ds_read_b128 v[242:245], v246 offset:3072
	s_waitcnt vmcnt(6) lgkmcnt(3)
	v_mfma_f32_16x16x32_bf16 v[112:115], v[128:131], v[196:199], v[112:115]
	v_mfma_f32_16x16x32_bf16 v[120:123], v[132:135], v[196:199], v[120:123]
	v_mfma_f32_16x16x32_bf16 v[48:51], v[136:139], v[196:199], v[48:51]
	v_mfma_f32_16x16x32_bf16 v[56:59], v[140:143], v[196:199], v[56:59]
	ds_read_b128 v[196:199], v246 offset:4096
	s_waitcnt lgkmcnt(3)
	v_mfma_f32_16x16x32_bf16 v[116:119], v[128:131], v[200:203], v[116:119]
	v_mfma_f32_16x16x32_bf16 v[124:127], v[132:135], v[200:203], v[124:127]
	v_mfma_f32_16x16x32_bf16 v[52:55], v[136:139], v[200:203], v[52:55]
	v_mfma_f32_16x16x32_bf16 v[60:63], v[140:143], v[200:203], v[60:63]
	ds_read_b128 v[200:203], v246 offset:5120
	s_waitcnt lgkmcnt(3)
	v_mfma_f32_16x16x32_bf16 v[96:99], v[128:131], v[204:207], v[96:99]
	v_mfma_f32_16x16x32_bf16 v[104:107], v[132:135], v[204:207], v[104:107]
	v_mfma_f32_16x16x32_bf16 v[32:35], v[136:139], v[204:207], v[32:35]
	v_mfma_f32_16x16x32_bf16 v[40:43], v[140:143], v[204:207], v[40:43]
	ds_read_b128 v[204:207], v246 offset:6144
	s_waitcnt lgkmcnt(3)
	v_mfma_f32_16x16x32_bf16 v[100:103], v[128:131], v[242:245], v[100:103]
	v_mfma_f32_16x16x32_bf16 v[108:111], v[132:135], v[242:245], v[108:111]
	v_mfma_f32_16x16x32_bf16 v[36:39], v[136:139], v[242:245], v[36:39]
	v_mfma_f32_16x16x32_bf16 v[44:47], v[140:143], v[242:245], v[44:47]
	ds_read_b128 v[242:245], v246 offset:7168
	s_waitcnt lgkmcnt(3)
	v_mfma_f32_16x16x32_bf16 v[80:83], v[128:131], v[196:199], v[80:83]
	v_mfma_f32_16x16x32_bf16 v[88:91], v[132:135], v[196:199], v[88:91]
	v_mfma_f32_16x16x32_bf16 v[16:19], v[136:139], v[196:199], v[16:19]
	v_mfma_f32_16x16x32_bf16 v[24:27], v[140:143], v[196:199], v[24:27]
	s_waitcnt lgkmcnt(2)
	v_mfma_f32_16x16x32_bf16 v[84:87], v[128:131], v[200:203], v[84:87]
	v_mfma_f32_16x16x32_bf16 v[92:95], v[132:135], v[200:203], v[92:95]
	v_mfma_f32_16x16x32_bf16 v[20:23], v[136:139], v[200:203], v[20:23]
	v_mfma_f32_16x16x32_bf16 v[28:31], v[140:143], v[200:203], v[28:31]
	s_waitcnt lgkmcnt(1)
	v_mfma_f32_16x16x32_bf16 v[64:67], v[128:131], v[204:207], v[64:67]
	v_mfma_f32_16x16x32_bf16 v[72:75], v[132:135], v[204:207], v[72:75]
	v_mfma_f32_16x16x32_bf16 v[0:3], v[136:139], v[204:207], v[0:3]
	v_mfma_f32_16x16x32_bf16 v[8:11], v[140:143], v[204:207], v[8:11]
	s_waitcnt lgkmcnt(0)
	v_mfma_f32_16x16x32_bf16 v[68:71], v[128:131], v[242:245], v[68:71]
	v_mfma_f32_16x16x32_bf16 v[76:79], v[132:135], v[242:245], v[76:79]
	v_mfma_f32_16x16x32_bf16 v[4:7], v[136:139], v[242:245], v[4:7]
	v_mfma_f32_16x16x32_bf16 v[12:15], v[140:143], v[242:245], v[12:15]
	s_waitcnt vmcnt(4)
	s_barrier
	ds_read_b128 v[196:199], v246 offset:8192
	ds_read_b128 v[200:203], v246 offset:9216
	ds_read_b128 v[204:207], v246 offset:10240
	ds_read_b128 v[242:245], v246 offset:11264
	s_waitcnt vmcnt(0) lgkmcnt(3)
	v_mfma_f32_16x16x32_bf16 v[112:115], v[144:147], v[196:199], v[112:115]
	v_mfma_f32_16x16x32_bf16 v[120:123], v[148:151], v[196:199], v[120:123]
	v_mfma_f32_16x16x32_bf16 v[48:51], v[152:155], v[196:199], v[48:51]
	v_mfma_f32_16x16x32_bf16 v[56:59], v[156:159], v[196:199], v[56:59]
	ds_read_b128 v[196:199], v246 offset:12288
	s_waitcnt lgkmcnt(3)
	v_mfma_f32_16x16x32_bf16 v[116:119], v[144:147], v[200:203], v[116:119]
	v_mfma_f32_16x16x32_bf16 v[124:127], v[148:151], v[200:203], v[124:127]
	v_mfma_f32_16x16x32_bf16 v[52:55], v[152:155], v[200:203], v[52:55]
	v_mfma_f32_16x16x32_bf16 v[60:63], v[156:159], v[200:203], v[60:63]
	ds_read_b128 v[200:203], v246 offset:13312
	s_waitcnt lgkmcnt(3)
	v_mfma_f32_16x16x32_bf16 v[96:99], v[144:147], v[204:207], v[96:99]
	v_mfma_f32_16x16x32_bf16 v[104:107], v[148:151], v[204:207], v[104:107]
	v_mfma_f32_16x16x32_bf16 v[32:35], v[152:155], v[204:207], v[32:35]
	v_mfma_f32_16x16x32_bf16 v[40:43], v[156:159], v[204:207], v[40:43]
	ds_read_b128 v[204:207], v246 offset:14336
	s_waitcnt lgkmcnt(3)
	v_mfma_f32_16x16x32_bf16 v[100:103], v[144:147], v[242:245], v[100:103]
	v_mfma_f32_16x16x32_bf16 v[108:111], v[148:151], v[242:245], v[108:111]
	v_mfma_f32_16x16x32_bf16 v[36:39], v[152:155], v[242:245], v[36:39]
	v_mfma_f32_16x16x32_bf16 v[44:47], v[156:159], v[242:245], v[44:47]
	ds_read_b128 v[242:245], v246 offset:15360
	v_permlane16_swap_b32_e32 v112, v116
	v_permlane16_swap_b32_e32 v113, v117
	v_permlane16_swap_b32_e32 v114, v118
	v_permlane16_swap_b32_e32 v115, v119
	v_permlane16_swap_b32_e32 v120, v124
	v_permlane16_swap_b32_e32 v121, v125
	v_permlane16_swap_b32_e32 v122, v126
	v_permlane16_swap_b32_e32 v123, v127
	v_permlane16_swap_b32_e32 v48, v52
	v_permlane16_swap_b32_e32 v49, v53
	v_permlane16_swap_b32_e32 v50, v54
	v_permlane16_swap_b32_e32 v51, v55
	v_permlane16_swap_b32_e32 v56, v60
	v_permlane16_swap_b32_e32 v57, v61
	v_permlane16_swap_b32_e32 v58, v62
	v_permlane16_swap_b32_e32 v59, v63
	v_permlane32_swap_b32_e32 v112, v116
	v_permlane32_swap_b32_e32 v113, v117
	v_permlane32_swap_b32_e32 v114, v118
	v_permlane32_swap_b32_e32 v115, v119
	v_permlane32_swap_b32_e32 v120, v124
	v_permlane32_swap_b32_e32 v121, v125
	v_permlane32_swap_b32_e32 v122, v126
	v_permlane32_swap_b32_e32 v123, v127
	v_permlane32_swap_b32_e32 v48, v52
	v_permlane32_swap_b32_e32 v49, v53
	v_permlane32_swap_b32_e32 v50, v54
	v_permlane32_swap_b32_e32 v51, v55
	v_permlane32_swap_b32_e32 v56, v60
	v_permlane32_swap_b32_e32 v57, v61
	v_permlane32_swap_b32_e32 v58, v62
	v_permlane32_swap_b32_e32 v59, v63
	s_waitcnt lgkmcnt(3)
	v_mfma_f32_16x16x32_bf16 v[80:83], v[144:147], v[196:199], v[80:83]
	v_mfma_f32_16x16x32_bf16 v[88:91], v[148:151], v[196:199], v[88:91]
	v_mfma_f32_16x16x32_bf16 v[16:19], v[152:155], v[196:199], v[16:19]
	v_mfma_f32_16x16x32_bf16 v[24:27], v[156:159], v[196:199], v[24:27]
	s_waitcnt lgkmcnt(2)
	v_mfma_f32_16x16x32_bf16 v[84:87], v[144:147], v[200:203], v[84:87]
	v_mfma_f32_16x16x32_bf16 v[92:95], v[148:151], v[200:203], v[92:95]
	v_mfma_f32_16x16x32_bf16 v[20:23], v[152:155], v[200:203], v[20:23]
	v_mfma_f32_16x16x32_bf16 v[28:31], v[156:159], v[200:203], v[28:31]
	v_permlane16_swap_b32_e32 v96, v100
	v_permlane16_swap_b32_e32 v97, v101
	v_permlane16_swap_b32_e32 v98, v102
	v_permlane16_swap_b32_e32 v99, v103
	v_permlane16_swap_b32_e32 v104, v108
	v_permlane16_swap_b32_e32 v105, v109
	v_permlane16_swap_b32_e32 v106, v110
	v_permlane16_swap_b32_e32 v107, v111
	v_permlane16_swap_b32_e32 v32, v36
	v_permlane16_swap_b32_e32 v33, v37
	v_permlane16_swap_b32_e32 v34, v38
	v_permlane16_swap_b32_e32 v35, v39
	v_permlane16_swap_b32_e32 v40, v44
	v_permlane16_swap_b32_e32 v41, v45
	v_permlane16_swap_b32_e32 v42, v46
	v_permlane16_swap_b32_e32 v43, v47
	v_permlane32_swap_b32_e32 v96, v100
	v_permlane32_swap_b32_e32 v97, v101
	v_permlane32_swap_b32_e32 v98, v102
	v_permlane32_swap_b32_e32 v99, v103
	v_permlane32_swap_b32_e32 v104, v108
	v_permlane32_swap_b32_e32 v105, v109
	v_permlane32_swap_b32_e32 v106, v110
	v_permlane32_swap_b32_e32 v107, v111
	v_permlane32_swap_b32_e32 v32, v36
	v_permlane32_swap_b32_e32 v33, v37
	v_permlane32_swap_b32_e32 v34, v38
	v_permlane32_swap_b32_e32 v35, v39
	v_permlane32_swap_b32_e32 v40, v44
	v_permlane32_swap_b32_e32 v41, v45
	v_permlane32_swap_b32_e32 v42, v46
	v_permlane32_swap_b32_e32 v43, v47
	s_waitcnt lgkmcnt(1)
	v_mfma_f32_16x16x32_bf16 v[64:67], v[144:147], v[204:207], v[64:67]
	v_mfma_f32_16x16x32_bf16 v[72:75], v[148:151], v[204:207], v[72:75]
	v_mfma_f32_16x16x32_bf16 v[0:3], v[152:155], v[204:207], v[0:3]
	v_mfma_f32_16x16x32_bf16 v[8:11], v[156:159], v[204:207], v[8:11]
	s_waitcnt lgkmcnt(0)
	v_mfma_f32_16x16x32_bf16 v[68:71], v[144:147], v[242:245], v[68:71]
	v_mfma_f32_16x16x32_bf16 v[76:79], v[148:151], v[242:245], v[76:79]
	v_mfma_f32_16x16x32_bf16 v[4:7], v[152:155], v[242:245], v[4:7]
	v_mfma_f32_16x16x32_bf16 v[12:15], v[156:159], v[242:245], v[12:15]
	v_permlane16_swap_b32_e32 v80, v84
	v_permlane16_swap_b32_e32 v81, v85
	v_permlane16_swap_b32_e32 v82, v86
	v_permlane16_swap_b32_e32 v83, v87
	v_permlane16_swap_b32_e32 v88, v92
	v_permlane16_swap_b32_e32 v89, v93
	v_permlane16_swap_b32_e32 v90, v94
	v_permlane16_swap_b32_e32 v91, v95
	v_permlane16_swap_b32_e32 v16, v20
	v_permlane16_swap_b32_e32 v17, v21
	v_permlane16_swap_b32_e32 v18, v22
	v_permlane16_swap_b32_e32 v19, v23
	v_permlane16_swap_b32_e32 v24, v28
	v_permlane16_swap_b32_e32 v25, v29
	v_permlane16_swap_b32_e32 v26, v30
	v_permlane16_swap_b32_e32 v27, v31
	v_permlane32_swap_b32_e32 v80, v84
	v_permlane32_swap_b32_e32 v81, v85
	v_permlane32_swap_b32_e32 v82, v86
	v_permlane32_swap_b32_e32 v83, v87
	v_permlane32_swap_b32_e32 v88, v92
	v_permlane32_swap_b32_e32 v89, v93
	v_permlane32_swap_b32_e32 v90, v94
	v_permlane32_swap_b32_e32 v91, v95
	v_permlane32_swap_b32_e32 v16, v20
	v_permlane32_swap_b32_e32 v17, v21
	v_permlane32_swap_b32_e32 v18, v22
	v_permlane32_swap_b32_e32 v19, v23
	v_permlane32_swap_b32_e32 v24, v28
	v_permlane32_swap_b32_e32 v25, v29
	v_permlane32_swap_b32_e32 v26, v30
	v_permlane32_swap_b32_e32 v27, v31
	s_barrier
	s_nop 7
	v_permlane16_swap_b32_e32 v64, v68
	v_permlane16_swap_b32_e32 v65, v69
	v_permlane16_swap_b32_e32 v66, v70
	v_permlane16_swap_b32_e32 v67, v71
	v_permlane16_swap_b32_e32 v72, v76
	v_permlane16_swap_b32_e32 v73, v77
	v_permlane16_swap_b32_e32 v74, v78
	v_permlane16_swap_b32_e32 v75, v79
	v_permlane16_swap_b32_e32 v0, v4
	v_permlane16_swap_b32_e32 v1, v5
	v_permlane16_swap_b32_e32 v2, v6
	v_permlane16_swap_b32_e32 v3, v7
	v_permlane16_swap_b32_e32 v8, v12
	v_permlane16_swap_b32_e32 v9, v13
	v_permlane16_swap_b32_e32 v10, v14
	v_permlane16_swap_b32_e32 v11, v15
	v_permlane32_swap_b32_e32 v64, v68
	v_permlane32_swap_b32_e32 v65, v69
	v_permlane32_swap_b32_e32 v66, v70
	v_permlane32_swap_b32_e32 v67, v71
	v_permlane32_swap_b32_e32 v72, v76
	v_permlane32_swap_b32_e32 v73, v77
	v_permlane32_swap_b32_e32 v74, v78
	v_permlane32_swap_b32_e32 v75, v79
	v_permlane32_swap_b32_e32 v0, v4
	v_permlane32_swap_b32_e32 v1, v5
	v_permlane32_swap_b32_e32 v2, v6
	v_permlane32_swap_b32_e32 v3, v7
	v_permlane32_swap_b32_e32 v8, v12
	v_permlane32_swap_b32_e32 v9, v13
	v_permlane32_swap_b32_e32 v10, v14
	v_permlane32_swap_b32_e32 v11, v15
	s_waitcnt vmcnt(0)
	s_waitcnt vmcnt(0)
	v_and_b32_e32 v188, 63, v179
	v_lshrrev_b32_e32 v189, 6, v179
	v_mul_u32_u24_e32 v249, 0x2400, v189
	v_mov_b32_e32 v250, v249
	v_lshrrev_b32_e32 v251, 5, v188
	v_mul_u32_u24_e32 v251, 0x440, v251
	v_add_u32_e32 v249, v249, v251
	v_and_b32_e32 v251, 31, v188
	v_lshl_add_u32 v249, v251, 2, v249
	v_lshrrev_b32_e32 v237, 4, v188
	v_mul_u32_u24_e32 v251, 0x110, v237
	v_add_u32_e32 v250, v250, v251
	v_and_b32_e32 v251, 15, v188
	v_lshlrev_b32_e32 v251, 4, v251
	v_add_u32_e32 v250, v250, v251
	v_lshl_add_u32 v237, v189, 6, v237
	v_lshl_add_u32 v237, v237, 12, v251
	v_add_u32_e32 v238, 16384, v237
	v_add_u32_e32 v239, 32768, v237
	v_add_u32_e32 v240, 49152, v237
	v_add_u32_e32 v241, 65536, v237
	v_add_u32_e32 v242, 81920, v237
	v_add_u32_e32 v243, 98304, v237
	v_add_u32_e32 v248, 114688, v237
	s_lshl_b32 s16, s8, 8
	s_lshl_b32 s18, s2, 9
	s_lshr_b32 s19, s8, 4
	v_readlane_b32 s12, v254, 38
	v_readlane_b32 s13, v254, 37
	v_readlane_b32 s14, v253, 46
	v_readlane_b32 s15, v253, 47
	v_readlane_b32 s22, v254, 40
	v_readlane_b32 s23, v254, 39
	s_add_i32 s17, s16, 0xffff8000
	s_cmpk_lt_u32 s8, 0x80
	s_cselect_b32 s12, s12, s22
	s_cselect_b32 s13, s13, s23
	s_cselect_b32 s14, s14, s62
	s_cselect_b32 s15, s15, s63
	s_cselect_b32 s19, s19, 8
	s_cselect_b32 s16, s16, s17
	s_mov_b32 s17, 0
	s_lshl_b64 s[16:17], s[16:17], 12
	s_add_u32 s16, s16, s18
	s_addc_u32 s17, s17, 0
	s_add_u32 s12, s12, s16
	s_addc_u32 s13, s13, s17
	s_add_u32 s14, s14, s16
	s_addc_u32 s15, s15, s17
	s_mul_i32 s19, s19, 0x6000
	s_add_u32 s20, s0, s19
	s_addc_u32 s21, s1, 0
	s_add_u32 s20, s20, s18
	s_addc_u32 s21, s21, 0
	global_load_dwordx4 v[244:247], v251, s[20:21]
	global_load_dwordx4 v[160:163], v237, s[12:13]
	global_load_dwordx4 v[164:167], v238, s[12:13]
	global_load_dwordx4 v[168:171], v239, s[12:13]
	global_load_dwordx4 v[172:175], v240, s[12:13]
	global_load_dwordx4 v[196:199], v241, s[12:13]
	global_load_dwordx4 v[200:203], v242, s[12:13]
	global_load_dwordx4 v[204:207], v243, s[12:13]
	global_load_dwordx4 v[184:187], v248, s[12:13]
	ds_write_b32 v249, v112
	ds_write_b32 v249, v113 offset:272
	ds_write_b32 v249, v114 offset:544
	ds_write_b32 v249, v115 offset:816
	ds_write_b32 v249, v116 offset:2176
	ds_write_b32 v249, v117 offset:2448
	ds_write_b32 v249, v118 offset:2720
	ds_write_b32 v249, v119 offset:2992
	ds_write_b32 v249, v120 offset:4352
	ds_write_b32 v249, v121 offset:4624
	ds_write_b32 v249, v122 offset:4896
	ds_write_b32 v249, v123 offset:5168
	ds_write_b32 v249, v124 offset:6528
	ds_write_b32 v249, v125 offset:6800
	ds_write_b32 v249, v126 offset:7072
	ds_write_b32 v249, v127 offset:7344
	ds_write_b32 v249, v96 offset:128
	ds_write_b32 v249, v97 offset:400
	ds_write_b32 v249, v98 offset:672
	ds_write_b32 v249, v99 offset:944
	ds_write_b32 v249, v100 offset:2304
	ds_write_b32 v249, v101 offset:2576
	ds_write_b32 v249, v102 offset:2848
	ds_write_b32 v249, v103 offset:3120
	ds_write_b32 v249, v104 offset:4480
	ds_write_b32 v249, v105 offset:4752
	ds_write_b32 v249, v106 offset:5024
	ds_write_b32 v249, v107 offset:5296
	ds_write_b32 v249, v108 offset:6656
	ds_write_b32 v249, v109 offset:6928
	ds_write_b32 v249, v110 offset:7200
	ds_write_b32 v249, v111 offset:7472
	s_waitcnt lgkmcnt(0)
	ds_read_b128 v[128:131], v250
	ds_read_b128 v[132:135], v250 offset:1088
	ds_read_b128 v[136:139], v250 offset:2176
	ds_read_b128 v[140:143], v250 offset:3264
	ds_read_b128 v[144:147], v250 offset:4352
	ds_read_b128 v[148:151], v250 offset:5440
	ds_read_b128 v[152:155], v250 offset:6528
	ds_read_b128 v[156:159], v250 offset:7616
	s_waitcnt vmcnt(7) lgkmcnt(7)
	v_fma_f32 v128, v244, v128, v160
	v_fma_f32 v129, v245, v129, v161
	v_fma_f32 v130, v246, v130, v162
	v_fma_f32 v131, v247, v131, v163
	global_store_dwordx4 v237, v[128:131], s[14:15]
	s_waitcnt vmcnt(7) lgkmcnt(6)
	v_fma_f32 v132, v244, v132, v164
	v_fma_f32 v133, v245, v133, v165
	v_fma_f32 v134, v246, v134, v166
	v_fma_f32 v135, v247, v135, v167
	global_store_dwordx4 v238, v[132:135], s[14:15]
	s_waitcnt vmcnt(7) lgkmcnt(5)
	v_fma_f32 v136, v244, v136, v168
	v_fma_f32 v137, v245, v137, v169
	v_fma_f32 v138, v246, v138, v170
	v_fma_f32 v139, v247, v139, v171
	global_store_dwordx4 v239, v[136:139], s[14:15]
	s_waitcnt vmcnt(7) lgkmcnt(4)
	v_fma_f32 v140, v244, v140, v172
	v_fma_f32 v141, v245, v141, v173
	v_fma_f32 v142, v246, v142, v174
	v_fma_f32 v143, v247, v143, v175
	global_store_dwordx4 v240, v[140:143], s[14:15]
	s_waitcnt vmcnt(7) lgkmcnt(3)
	v_fma_f32 v144, v244, v144, v196
	v_fma_f32 v145, v245, v145, v197
	v_fma_f32 v146, v246, v146, v198
	v_fma_f32 v147, v247, v147, v199
	global_store_dwordx4 v241, v[144:147], s[14:15]
	s_waitcnt vmcnt(7) lgkmcnt(2)
	v_fma_f32 v148, v244, v148, v200
	v_fma_f32 v149, v245, v149, v201
	v_fma_f32 v150, v246, v150, v202
	v_fma_f32 v151, v247, v151, v203
	global_store_dwordx4 v242, v[148:151], s[14:15]
	s_waitcnt vmcnt(7) lgkmcnt(1)
	v_fma_f32 v152, v244, v152, v204
	v_fma_f32 v153, v245, v153, v205
	v_fma_f32 v154, v246, v154, v206
	v_fma_f32 v155, v247, v155, v207
	global_store_dwordx4 v243, v[152:155], s[14:15]
	s_waitcnt vmcnt(7) lgkmcnt(0)
	v_fma_f32 v156, v244, v156, v184
	v_fma_f32 v157, v245, v157, v185
	v_fma_f32 v158, v246, v158, v186
	v_fma_f32 v159, v247, v159, v187
	global_store_dwordx4 v248, v[156:159], s[14:15]
	global_load_dwordx4 v[244:247], v251, s[20:21] offset:256
	global_load_dwordx4 v[160:163], v237, s[12:13] offset:256
	global_load_dwordx4 v[164:167], v238, s[12:13] offset:256
	global_load_dwordx4 v[168:171], v239, s[12:13] offset:256
	global_load_dwordx4 v[172:175], v240, s[12:13] offset:256
	global_load_dwordx4 v[196:199], v241, s[12:13] offset:256
	global_load_dwordx4 v[200:203], v242, s[12:13] offset:256
	global_load_dwordx4 v[204:207], v243, s[12:13] offset:256
	global_load_dwordx4 v[184:187], v248, s[12:13] offset:256
	ds_write_b32 v249, v80
	ds_write_b32 v249, v81 offset:272
	ds_write_b32 v249, v82 offset:544
	ds_write_b32 v249, v83 offset:816
	ds_write_b32 v249, v84 offset:2176
	ds_write_b32 v249, v85 offset:2448
	ds_write_b32 v249, v86 offset:2720
	ds_write_b32 v249, v87 offset:2992
	ds_write_b32 v249, v88 offset:4352
	ds_write_b32 v249, v89 offset:4624
	ds_write_b32 v249, v90 offset:4896
	ds_write_b32 v249, v91 offset:5168
	ds_write_b32 v249, v92 offset:6528
	ds_write_b32 v249, v93 offset:6800
	ds_write_b32 v249, v94 offset:7072
	ds_write_b32 v249, v95 offset:7344
	ds_write_b32 v249, v64 offset:128
	ds_write_b32 v249, v65 offset:400
	ds_write_b32 v249, v66 offset:672
	ds_write_b32 v249, v67 offset:944
	ds_write_b32 v249, v68 offset:2304
	ds_write_b32 v249, v69 offset:2576
	ds_write_b32 v249, v70 offset:2848
	ds_write_b32 v249, v71 offset:3120
	ds_write_b32 v249, v72 offset:4480
	ds_write_b32 v249, v73 offset:4752
	ds_write_b32 v249, v74 offset:5024
	ds_write_b32 v249, v75 offset:5296
	ds_write_b32 v249, v76 offset:6656
	ds_write_b32 v249, v77 offset:6928
	ds_write_b32 v249, v78 offset:7200
	ds_write_b32 v249, v79 offset:7472
	s_waitcnt lgkmcnt(0)
	ds_read_b128 v[128:131], v250
	ds_read_b128 v[132:135], v250 offset:1088
	ds_read_b128 v[136:139], v250 offset:2176
	ds_read_b128 v[140:143], v250 offset:3264
	ds_read_b128 v[144:147], v250 offset:4352
	ds_read_b128 v[148:151], v250 offset:5440
	ds_read_b128 v[152:155], v250 offset:6528
	ds_read_b128 v[156:159], v250 offset:7616
	s_waitcnt vmcnt(7) lgkmcnt(7)
	v_fma_f32 v128, v244, v128, v160
	v_fma_f32 v129, v245, v129, v161
	v_fma_f32 v130, v246, v130, v162
	v_fma_f32 v131, v247, v131, v163
	global_store_dwordx4 v237, v[128:131], s[14:15] offset:256
	s_waitcnt vmcnt(7) lgkmcnt(6)
	v_fma_f32 v132, v244, v132, v164
	v_fma_f32 v133, v245, v133, v165
	v_fma_f32 v134, v246, v134, v166
	v_fma_f32 v135, v247, v135, v167
	global_store_dwordx4 v238, v[132:135], s[14:15] offset:256
	s_waitcnt vmcnt(7) lgkmcnt(5)
	v_fma_f32 v136, v244, v136, v168
	v_fma_f32 v137, v245, v137, v169
	v_fma_f32 v138, v246, v138, v170
	v_fma_f32 v139, v247, v139, v171
	global_store_dwordx4 v239, v[136:139], s[14:15] offset:256
	s_waitcnt vmcnt(7) lgkmcnt(4)
	v_fma_f32 v140, v244, v140, v172
	v_fma_f32 v141, v245, v141, v173
	v_fma_f32 v142, v246, v142, v174
	v_fma_f32 v143, v247, v143, v175
	global_store_dwordx4 v240, v[140:143], s[14:15] offset:256
	s_waitcnt vmcnt(7) lgkmcnt(3)
	v_fma_f32 v144, v244, v144, v196
	v_fma_f32 v145, v245, v145, v197
	v_fma_f32 v146, v246, v146, v198
	v_fma_f32 v147, v247, v147, v199
	global_store_dwordx4 v241, v[144:147], s[14:15] offset:256
	s_waitcnt vmcnt(7) lgkmcnt(2)
	v_fma_f32 v148, v244, v148, v200
	v_fma_f32 v149, v245, v149, v201
	v_fma_f32 v150, v246, v150, v202
	v_fma_f32 v151, v247, v151, v203
	global_store_dwordx4 v242, v[148:151], s[14:15] offset:256
	s_waitcnt vmcnt(7) lgkmcnt(1)
	v_fma_f32 v152, v244, v152, v204
	v_fma_f32 v153, v245, v153, v205
	v_fma_f32 v154, v246, v154, v206
	v_fma_f32 v155, v247, v155, v207
	global_store_dwordx4 v243, v[152:155], s[14:15] offset:256
	s_waitcnt vmcnt(7) lgkmcnt(0)
	v_fma_f32 v156, v244, v156, v184
	v_fma_f32 v157, v245, v157, v185
	v_fma_f32 v158, v246, v158, v186
	v_fma_f32 v159, v247, v159, v187
	global_store_dwordx4 v248, v[156:159], s[14:15] offset:256
	s_add_u32 s12, s12, 0x20000
	s_addc_u32 s13, s13, 0
	s_add_u32 s14, s14, 0x20000
	s_addc_u32 s15, s15, 0
	global_load_dwordx4 v[244:247], v251, s[20:21]
	global_load_dwordx4 v[160:163], v237, s[12:13]
	global_load_dwordx4 v[164:167], v238, s[12:13]
	global_load_dwordx4 v[168:171], v239, s[12:13]
	global_load_dwordx4 v[172:175], v240, s[12:13]
	global_load_dwordx4 v[196:199], v241, s[12:13]
	global_load_dwordx4 v[200:203], v242, s[12:13]
	global_load_dwordx4 v[204:207], v243, s[12:13]
	global_load_dwordx4 v[184:187], v248, s[12:13]
	ds_write_b32 v249, v48
	ds_write_b32 v249, v49 offset:272
	ds_write_b32 v249, v50 offset:544
	ds_write_b32 v249, v51 offset:816
	ds_write_b32 v249, v52 offset:2176
	ds_write_b32 v249, v53 offset:2448
	ds_write_b32 v249, v54 offset:2720
	ds_write_b32 v249, v55 offset:2992
	ds_write_b32 v249, v56 offset:4352
	ds_write_b32 v249, v57 offset:4624
	ds_write_b32 v249, v58 offset:4896
	ds_write_b32 v249, v59 offset:5168
	ds_write_b32 v249, v60 offset:6528
	ds_write_b32 v249, v61 offset:6800
	ds_write_b32 v249, v62 offset:7072
	ds_write_b32 v249, v63 offset:7344
	ds_write_b32 v249, v32 offset:128
	ds_write_b32 v249, v33 offset:400
	ds_write_b32 v249, v34 offset:672
	ds_write_b32 v249, v35 offset:944
	ds_write_b32 v249, v36 offset:2304
	ds_write_b32 v249, v37 offset:2576
	ds_write_b32 v249, v38 offset:2848
	ds_write_b32 v249, v39 offset:3120
	ds_write_b32 v249, v40 offset:4480
	ds_write_b32 v249, v41 offset:4752
	ds_write_b32 v249, v42 offset:5024
	ds_write_b32 v249, v43 offset:5296
	ds_write_b32 v249, v44 offset:6656
	ds_write_b32 v249, v45 offset:6928
	ds_write_b32 v249, v46 offset:7200
	ds_write_b32 v249, v47 offset:7472
	s_waitcnt lgkmcnt(0)
	ds_read_b128 v[128:131], v250
	ds_read_b128 v[132:135], v250 offset:1088
	ds_read_b128 v[136:139], v250 offset:2176
	ds_read_b128 v[140:143], v250 offset:3264
	ds_read_b128 v[144:147], v250 offset:4352
	ds_read_b128 v[148:151], v250 offset:5440
	ds_read_b128 v[152:155], v250 offset:6528
	ds_read_b128 v[156:159], v250 offset:7616
	s_waitcnt vmcnt(7) lgkmcnt(7)
	v_fma_f32 v128, v244, v128, v160
	v_fma_f32 v129, v245, v129, v161
	v_fma_f32 v130, v246, v130, v162
	v_fma_f32 v131, v247, v131, v163
	global_store_dwordx4 v237, v[128:131], s[14:15]
	s_waitcnt vmcnt(7) lgkmcnt(6)
	v_fma_f32 v132, v244, v132, v164
	v_fma_f32 v133, v245, v133, v165
	v_fma_f32 v134, v246, v134, v166
	v_fma_f32 v135, v247, v135, v167
	global_store_dwordx4 v238, v[132:135], s[14:15]
	s_waitcnt vmcnt(7) lgkmcnt(5)
	v_fma_f32 v136, v244, v136, v168
	v_fma_f32 v137, v245, v137, v169
	v_fma_f32 v138, v246, v138, v170
	v_fma_f32 v139, v247, v139, v171
	global_store_dwordx4 v239, v[136:139], s[14:15]
	s_waitcnt vmcnt(7) lgkmcnt(4)
	v_fma_f32 v140, v244, v140, v172
	v_fma_f32 v141, v245, v141, v173
	v_fma_f32 v142, v246, v142, v174
	v_fma_f32 v143, v247, v143, v175
	global_store_dwordx4 v240, v[140:143], s[14:15]
	s_waitcnt vmcnt(7) lgkmcnt(3)
	v_fma_f32 v144, v244, v144, v196
	v_fma_f32 v145, v245, v145, v197
	v_fma_f32 v146, v246, v146, v198
	v_fma_f32 v147, v247, v147, v199
	global_store_dwordx4 v241, v[144:147], s[14:15]
	s_waitcnt vmcnt(7) lgkmcnt(2)
	v_fma_f32 v148, v244, v148, v200
	v_fma_f32 v149, v245, v149, v201
	v_fma_f32 v150, v246, v150, v202
	v_fma_f32 v151, v247, v151, v203
	global_store_dwordx4 v242, v[148:151], s[14:15]
	s_waitcnt vmcnt(7) lgkmcnt(1)
	v_fma_f32 v152, v244, v152, v204
	v_fma_f32 v153, v245, v153, v205
	v_fma_f32 v154, v246, v154, v206
	v_fma_f32 v155, v247, v155, v207
	global_store_dwordx4 v243, v[152:155], s[14:15]
	s_waitcnt vmcnt(7) lgkmcnt(0)
	v_fma_f32 v156, v244, v156, v184
	v_fma_f32 v157, v245, v157, v185
	v_fma_f32 v158, v246, v158, v186
	v_fma_f32 v159, v247, v159, v187
	global_store_dwordx4 v248, v[156:159], s[14:15]
	global_load_dwordx4 v[244:247], v251, s[20:21] offset:256
	global_load_dwordx4 v[160:163], v237, s[12:13] offset:256
	global_load_dwordx4 v[164:167], v238, s[12:13] offset:256
	global_load_dwordx4 v[168:171], v239, s[12:13] offset:256
	global_load_dwordx4 v[172:175], v240, s[12:13] offset:256
	global_load_dwordx4 v[196:199], v241, s[12:13] offset:256
	global_load_dwordx4 v[200:203], v242, s[12:13] offset:256
	global_load_dwordx4 v[204:207], v243, s[12:13] offset:256
	global_load_dwordx4 v[184:187], v248, s[12:13] offset:256
	ds_write_b32 v249, v16
	ds_write_b32 v249, v17 offset:272
	ds_write_b32 v249, v18 offset:544
	ds_write_b32 v249, v19 offset:816
	ds_write_b32 v249, v20 offset:2176
	ds_write_b32 v249, v21 offset:2448
	ds_write_b32 v249, v22 offset:2720
	ds_write_b32 v249, v23 offset:2992
	ds_write_b32 v249, v24 offset:4352
	ds_write_b32 v249, v25 offset:4624
	ds_write_b32 v249, v26 offset:4896
	ds_write_b32 v249, v27 offset:5168
	ds_write_b32 v249, v28 offset:6528
	ds_write_b32 v249, v29 offset:6800
	ds_write_b32 v249, v30 offset:7072
	ds_write_b32 v249, v31 offset:7344
	ds_write_b32 v249, v0 offset:128
	ds_write_b32 v249, v1 offset:400
	ds_write_b32 v249, v2 offset:672
	ds_write_b32 v249, v3 offset:944
	ds_write_b32 v249, v4 offset:2304
	ds_write_b32 v249, v5 offset:2576
	ds_write_b32 v249, v6 offset:2848
	ds_write_b32 v249, v7 offset:3120
	ds_write_b32 v249, v8 offset:4480
	ds_write_b32 v249, v9 offset:4752
	ds_write_b32 v249, v10 offset:5024
	ds_write_b32 v249, v11 offset:5296
	ds_write_b32 v249, v12 offset:6656
	ds_write_b32 v249, v13 offset:6928
	ds_write_b32 v249, v14 offset:7200
	ds_write_b32 v249, v15 offset:7472
	s_waitcnt lgkmcnt(0)
	ds_read_b128 v[128:131], v250
	ds_read_b128 v[132:135], v250 offset:1088
	ds_read_b128 v[136:139], v250 offset:2176
	ds_read_b128 v[140:143], v250 offset:3264
	ds_read_b128 v[144:147], v250 offset:4352
	ds_read_b128 v[148:151], v250 offset:5440
	ds_read_b128 v[152:155], v250 offset:6528
	ds_read_b128 v[156:159], v250 offset:7616
	s_waitcnt vmcnt(7) lgkmcnt(7)
	v_fma_f32 v128, v244, v128, v160
	v_fma_f32 v129, v245, v129, v161
	v_fma_f32 v130, v246, v130, v162
	v_fma_f32 v131, v247, v131, v163
	global_store_dwordx4 v237, v[128:131], s[14:15] offset:256
	s_waitcnt vmcnt(7) lgkmcnt(6)
	v_fma_f32 v132, v244, v132, v164
	v_fma_f32 v133, v245, v133, v165
	v_fma_f32 v134, v246, v134, v166
	v_fma_f32 v135, v247, v135, v167
	global_store_dwordx4 v238, v[132:135], s[14:15] offset:256
	s_waitcnt vmcnt(7) lgkmcnt(5)
	v_fma_f32 v136, v244, v136, v168
	v_fma_f32 v137, v245, v137, v169
	v_fma_f32 v138, v246, v138, v170
	v_fma_f32 v139, v247, v139, v171
	global_store_dwordx4 v239, v[136:139], s[14:15] offset:256
	s_waitcnt vmcnt(7) lgkmcnt(4)
	v_fma_f32 v140, v244, v140, v172
	v_fma_f32 v141, v245, v141, v173
	v_fma_f32 v142, v246, v142, v174
	v_fma_f32 v143, v247, v143, v175
	global_store_dwordx4 v240, v[140:143], s[14:15] offset:256
	s_waitcnt vmcnt(7) lgkmcnt(3)
	v_fma_f32 v144, v244, v144, v196
	v_fma_f32 v145, v245, v145, v197
	v_fma_f32 v146, v246, v146, v198
	v_fma_f32 v147, v247, v147, v199
	global_store_dwordx4 v241, v[144:147], s[14:15] offset:256
	s_waitcnt vmcnt(7) lgkmcnt(2)
	v_fma_f32 v148, v244, v148, v200
	v_fma_f32 v149, v245, v149, v201
	v_fma_f32 v150, v246, v150, v202
	v_fma_f32 v151, v247, v151, v203
	global_store_dwordx4 v242, v[148:151], s[14:15] offset:256
	s_waitcnt vmcnt(7) lgkmcnt(1)
	v_fma_f32 v152, v244, v152, v204
	v_fma_f32 v153, v245, v153, v205
	v_fma_f32 v154, v246, v154, v206
	v_fma_f32 v155, v247, v155, v207
	global_store_dwordx4 v243, v[152:155], s[14:15] offset:256
	s_waitcnt vmcnt(7) lgkmcnt(0)
	v_fma_f32 v156, v244, v156, v184
	v_fma_f32 v157, v245, v157, v185
	v_fma_f32 v158, v246, v158, v186
	v_fma_f32 v159, v247, v159, v187
	global_store_dwordx4 v248, v[156:159], s[14:15] offset:256
	s_waitcnt lgkmcnt(0)
	v_readlane_b32 s16, v254, 11
	s_andn2_b32 s17, s26, 63
	s_add_i32 s4, s4, s16
	s_cmp_lt_i32 s4, s17
	s_cbranch_scc0 .Lhx_out_left
	s_barrier
	s_branch .LBB0_923
.Lhx_out_left:
	s_and_b32 s18, s26, 63
	s_cbranch_scc0 .Lhx_out_done
	v_readlane_b32 s19, v253, 0
	s_lshl_b32 s18, s18, 1
	s_ashr_i32 s19, s19, 3
	s_cmp_lt_i32 s19, s18
	s_cbranch_scc0 .Lhx_out_done
	s_mov_b32 s100, 1
	s_and_b32 s101, s19, 1
	s_lshr_b32 s19, s19, 1
	s_add_i32 s4, s17, s19
	s_barrier
	s_branch .LBB0_923

.Lhx_out_half:
	v_bfe_u32 v247, v181, 4, 2
	v_lshlrev_b32_e32 v247, 1, v247
	v_mov_b32_e32 v176, 0x78
	v_lshrrev_b32_e32 v247, v247, v176
	v_and_b32_e32 v247, 3, v247
	v_and_b32_e32 v246, 3, v181
	v_xor_b32_e32 v247, v247, v246
	v_lshlrev_b32_e32 v247, 4, v247
	v_and_b32_e32 v188, 0xffffffcf, v186
	v_or_b32_e32 v188, v188, v247
	v_mov_b32_e32 v189, v187
	v_lshrrev_b32_e32 v176, 6, v181
	v_lshlrev_b32_e32 v247, 11, v176
	v_lshlrev_b32_e32 v176, 10, v176
	v_lshl_add_u64 v[188:189], v[188:189], 0, v[176:177]
	v_readfirstlane_b32 vcc_lo, v247
	v_bfe_u32 v247, v181, 4, 1
	v_lshlrev_b32_e32 v176, 9, v183
	v_lshl_add_u32 v176, v247, 8, v176
	v_lshl_add_u64 v[184:185], v[184:185], 0, v[176:177]
	v_mov_b32_e32 v176, s41
	v_lshl_add_u64 v[186:187], v[184:185], 0, v[176:177]
	v_mov_b32_e32 v176, 0x78
	v_bfe_u32 v247, v181, 2, 2
	v_lshlrev_b32_e32 v247, 1, v247
	v_lshrrev_b32_e32 v247, v247, v176
	v_and_b32_e32 v247, 3, v247
	v_bfe_u32 v246, v181, 4, 2
	v_xor_b32_e32 v247, v247, v246
	v_lshlrev_b32_e32 v247, 4, v247
	v_and_b32_e32 v246, 15, v181
	v_lshl_add_u32 v246, v246, 6, v247
	s_cmp_eq_u32 s101, 1
	s_cbranch_scc0 .Lg16_outh_a0
	v_mov_b32_e32 v184, v186
	v_mov_b32_e32 v185, v187
.Lg16_outh_a0:
	s_mov_b32 s96, 0
	s_mov_b32 m0, vcc_lo
	v_lshl_add_u64 v[160:161], v[188:189], 0, s[96:97]
	global_load_lds_dwordx4 v[160:161], off
	global_load_lds_dwordx4 v[160:161], off offset:1024
	s_mov_b32 s96, 0
	v_lshl_add_u64 v[248:249], v[184:185], 0, s[96:97]
	v_lshl_add_u64 v[250:251], v[186:187], 0, s[96:97]
	global_load_dwordx4 v[128:131], v[248:249], off
	global_load_dwordx4 v[132:135], v[248:249], off offset:256
	s_movk_i32 s96, 0x2000
	s_add_i32 m0, vcc_lo, 8192
	v_lshl_add_u64 v[160:161], v[188:189], 0, s[96:97]
	global_load_lds_dwordx4 v[160:161], off
	global_load_lds_dwordx4 v[160:161], off offset:1024
	s_movk_i32 s96, 0x800
	v_lshl_add_u64 v[248:249], v[184:185], 0, s[96:97]
	v_lshl_add_u64 v[250:251], v[186:187], 0, s[96:97]
	global_load_dwordx4 v[144:147], v[248:249], off
	global_load_dwordx4 v[148:151], v[248:249], off offset:256
	v_mov_b32_e32 v0, 0
	v_mov_b32_e32 v1, 0
	v_mov_b32_e32 v2, 0
	v_mov_b32_e32 v3, 0
	v_mov_b32_e32 v4, 0
	v_mov_b32_e32 v5, 0
	v_mov_b32_e32 v6, 0
	v_mov_b32_e32 v7, 0
	v_mov_b32_e32 v8, 0
	v_mov_b32_e32 v9, 0
	v_mov_b32_e32 v10, 0
	v_mov_b32_e32 v11, 0
	v_mov_b32_e32 v12, 0
	v_mov_b32_e32 v13, 0
	v_mov_b32_e32 v14, 0
	v_mov_b32_e32 v15, 0
	v_mov_b32_e32 v16, 0
	v_mov_b32_e32 v17, 0
	v_mov_b32_e32 v18, 0
	v_mov_b32_e32 v19, 0
	v_mov_b32_e32 v20, 0
	v_mov_b32_e32 v21, 0
	v_mov_b32_e32 v22, 0
	v_mov_b32_e32 v23, 0
	v_mov_b32_e32 v24, 0
	v_mov_b32_e32 v25, 0
	v_mov_b32_e32 v26, 0
	v_mov_b32_e32 v27, 0
	v_mov_b32_e32 v28, 0
	v_mov_b32_e32 v29, 0
	v_mov_b32_e32 v30, 0
	v_mov_b32_e32 v31, 0
	v_mov_b32_e32 v32, 0
	v_mov_b32_e32 v33, 0
	v_mov_b32_e32 v34, 0
	v_mov_b32_e32 v35, 0
	v_mov_b32_e32 v36, 0
	v_mov_b32_e32 v37, 0
	v_mov_b32_e32 v38, 0
	v_mov_b32_e32 v39, 0
	v_mov_b32_e32 v40, 0
	v_mov_b32_e32 v41, 0
	v_mov_b32_e32 v42, 0
	v_mov_b32_e32 v43, 0
	v_mov_b32_e32 v44, 0
	v_mov_b32_e32 v45, 0
	v_mov_b32_e32 v46, 0
	v_mov_b32_e32 v47, 0
	v_mov_b32_e32 v48, 0
	v_mov_b32_e32 v49, 0
	v_mov_b32_e32 v50, 0
	v_mov_b32_e32 v51, 0
	v_mov_b32_e32 v52, 0
	v_mov_b32_e32 v53, 0
	v_mov_b32_e32 v54, 0
	v_mov_b32_e32 v55, 0
	v_mov_b32_e32 v56, 0
	v_mov_b32_e32 v57, 0
	v_mov_b32_e32 v58, 0
	v_mov_b32_e32 v59, 0
	v_mov_b32_e32 v60, 0
	v_mov_b32_e32 v61, 0
	v_mov_b32_e32 v62, 0
	v_mov_b32_e32 v63, 0
	v_mov_b32_e32 v64, 0
	v_mov_b32_e32 v65, 0
	v_mov_b32_e32 v66, 0
	v_mov_b32_e32 v67, 0
	v_mov_b32_e32 v68, 0
	v_mov_b32_e32 v69, 0
	v_mov_b32_e32 v70, 0
	v_mov_b32_e32 v71, 0
	v_mov_b32_e32 v72, 0
	v_mov_b32_e32 v73, 0
	v_mov_b32_e32 v74, 0
	v_mov_b32_e32 v75, 0
	v_mov_b32_e32 v76, 0
	v_mov_b32_e32 v77, 0
	v_mov_b32_e32 v78, 0
	v_mov_b32_e32 v79, 0
	v_mov_b32_e32 v80, 0
	v_mov_b32_e32 v81, 0
	v_mov_b32_e32 v82, 0
	v_mov_b32_e32 v83, 0
	v_mov_b32_e32 v84, 0
	v_mov_b32_e32 v85, 0
	v_mov_b32_e32 v86, 0
	v_mov_b32_e32 v87, 0
	v_mov_b32_e32 v88, 0
	v_mov_b32_e32 v89, 0
	v_mov_b32_e32 v90, 0
	v_mov_b32_e32 v91, 0
	v_mov_b32_e32 v92, 0
	v_mov_b32_e32 v93, 0
	v_mov_b32_e32 v94, 0
	v_mov_b32_e32 v95, 0
	v_mov_b32_e32 v96, 0
	v_mov_b32_e32 v97, 0
	v_mov_b32_e32 v98, 0
	v_mov_b32_e32 v99, 0
	v_mov_b32_e32 v100, 0
	v_mov_b32_e32 v101, 0
	v_mov_b32_e32 v102, 0
	v_mov_b32_e32 v103, 0
	v_mov_b32_e32 v104, 0
	v_mov_b32_e32 v105, 0
	v_mov_b32_e32 v106, 0
	v_mov_b32_e32 v107, 0
	v_mov_b32_e32 v108, 0
	v_mov_b32_e32 v109, 0
	v_mov_b32_e32 v110, 0
	v_mov_b32_e32 v111, 0
	v_mov_b32_e32 v112, 0
	v_mov_b32_e32 v113, 0
	v_mov_b32_e32 v114, 0
	v_mov_b32_e32 v115, 0
	v_mov_b32_e32 v116, 0
	v_mov_b32_e32 v117, 0
	v_mov_b32_e32 v118, 0
	v_mov_b32_e32 v119, 0
	v_mov_b32_e32 v120, 0
	v_mov_b32_e32 v121, 0
	v_mov_b32_e32 v122, 0
	v_mov_b32_e32 v123, 0
	v_mov_b32_e32 v124, 0
	v_mov_b32_e32 v125, 0
	v_mov_b32_e32 v126, 0
	v_mov_b32_e32 v127, 0
	s_mov_b32 s3, 0
	s_waitcnt vmcnt(2)
	s_barrier
.Lg16_outh_k:
	s_add_i32 s9, s3, 2
	s_lshl_b32 s96, s9, 13
	s_add_i32 m0, vcc_lo, 16384
	v_lshl_add_u64 v[160:161], v[188:189], 0, s[96:97]
	global_load_lds_dwordx4 v[160:161], off
	global_load_lds_dwordx4 v[160:161], off offset:1024
	ds_read_b128 v[196:199], v246 offset:0
	ds_read_b128 v[200:203], v246 offset:1024
	ds_read_b128 v[204:207], v246 offset:2048
	ds_read_b128 v[242:245], v246 offset:3072
	s_add_i32 s9, s3, 2
	s_lshl_b32 s96, s9, 11
	v_lshl_add_u64 v[248:249], v[184:185], 0, s[96:97]
	v_lshl_add_u64 v[250:251], v[186:187], 0, s[96:97]
	s_waitcnt vmcnt(6) lgkmcnt(3)
	v_mfma_f32_16x16x32_bf16 v[112:115], v[128:131], v[196:199], v[112:115]
	v_mfma_f32_16x16x32_bf16 v[120:123], v[132:135], v[196:199], v[120:123]
	ds_read_b128 v[196:199], v246 offset:4096
	s_waitcnt lgkmcnt(3)
	v_mfma_f32_16x16x32_bf16 v[116:119], v[128:131], v[200:203], v[116:119]
	v_mfma_f32_16x16x32_bf16 v[124:127], v[132:135], v[200:203], v[124:127]
	ds_read_b128 v[200:203], v246 offset:5120
	s_waitcnt lgkmcnt(3)
	v_mfma_f32_16x16x32_bf16 v[96:99], v[128:131], v[204:207], v[96:99]
	v_mfma_f32_16x16x32_bf16 v[104:107], v[132:135], v[204:207], v[104:107]
	ds_read_b128 v[204:207], v246 offset:6144
	s_waitcnt lgkmcnt(3)
	v_mfma_f32_16x16x32_bf16 v[100:103], v[128:131], v[242:245], v[100:103]
	v_mfma_f32_16x16x32_bf16 v[108:111], v[132:135], v[242:245], v[108:111]
	ds_read_b128 v[242:245], v246 offset:7168
	s_waitcnt lgkmcnt(3)
	v_mfma_f32_16x16x32_bf16 v[80:83], v[128:131], v[196:199], v[80:83]
	v_mfma_f32_16x16x32_bf16 v[88:91], v[132:135], v[196:199], v[88:91]
	s_waitcnt lgkmcnt(2)
	v_mfma_f32_16x16x32_bf16 v[84:87], v[128:131], v[200:203], v[84:87]
	v_mfma_f32_16x16x32_bf16 v[92:95], v[132:135], v[200:203], v[92:95]
	s_waitcnt lgkmcnt(1)
	v_mfma_f32_16x16x32_bf16 v[64:67], v[128:131], v[204:207], v[64:67]
	v_mfma_f32_16x16x32_bf16 v[72:75], v[132:135], v[204:207], v[72:75]
	s_waitcnt lgkmcnt(0)
	v_mfma_f32_16x16x32_bf16 v[68:71], v[128:131], v[242:245], v[68:71]
	v_mfma_f32_16x16x32_bf16 v[76:79], v[132:135], v[242:245], v[76:79]
	global_load_dwordx4 v[128:131], v[248:249], off
	global_load_dwordx4 v[132:135], v[248:249], off offset:256
	s_waitcnt vmcnt(6)
	s_barrier
	s_add_i32 s9, s3, 3
	s_lshl_b32 s96, s9, 13
	s_mov_b32 m0, vcc_lo
	v_lshl_add_u64 v[160:161], v[188:189], 0, s[96:97]
	global_load_lds_dwordx4 v[160:161], off
	global_load_lds_dwordx4 v[160:161], off offset:1024
	ds_read_b128 v[196:199], v246 offset:8192
	ds_read_b128 v[200:203], v246 offset:9216
	ds_read_b128 v[204:207], v246 offset:10240
	ds_read_b128 v[242:245], v246 offset:11264
	s_add_i32 s9, s3, 3
	s_lshl_b32 s96, s9, 11
	v_lshl_add_u64 v[248:249], v[184:185], 0, s[96:97]
	v_lshl_add_u64 v[250:251], v[186:187], 0, s[96:97]
	s_waitcnt vmcnt(6) lgkmcnt(3)
	v_mfma_f32_16x16x32_bf16 v[112:115], v[144:147], v[196:199], v[112:115]
	v_mfma_f32_16x16x32_bf16 v[120:123], v[148:151], v[196:199], v[120:123]
	ds_read_b128 v[196:199], v246 offset:12288
	s_waitcnt lgkmcnt(3)
	v_mfma_f32_16x16x32_bf16 v[116:119], v[144:147], v[200:203], v[116:119]
	v_mfma_f32_16x16x32_bf16 v[124:127], v[148:151], v[200:203], v[124:127]
	ds_read_b128 v[200:203], v246 offset:13312
	s_waitcnt lgkmcnt(3)
	v_mfma_f32_16x16x32_bf16 v[96:99], v[144:147], v[204:207], v[96:99]
	v_mfma_f32_16x16x32_bf16 v[104:107], v[148:151], v[204:207], v[104:107]
	ds_read_b128 v[204:207], v246 offset:14336
	s_waitcnt lgkmcnt(3)
	v_mfma_f32_16x16x32_bf16 v[100:103], v[144:147], v[242:245], v[100:103]
	v_mfma_f32_16x16x32_bf16 v[108:111], v[148:151], v[242:245], v[108:111]
	ds_read_b128 v[242:245], v246 offset:15360
	s_waitcnt lgkmcnt(3)
	v_mfma_f32_16x16x32_bf16 v[80:83], v[144:147], v[196:199], v[80:83]
	v_mfma_f32_16x16x32_bf16 v[88:91], v[148:151], v[196:199], v[88:91]
	s_waitcnt lgkmcnt(2)
	v_mfma_f32_16x16x32_bf16 v[84:87], v[144:147], v[200:203], v[84:87]
	v_mfma_f32_16x16x32_bf16 v[92:95], v[148:151], v[200:203], v[92:95]
	s_waitcnt lgkmcnt(1)
	v_mfma_f32_16x16x32_bf16 v[64:67], v[144:147], v[204:207], v[64:67]
	v_mfma_f32_16x16x32_bf16 v[72:75], v[148:151], v[204:207], v[72:75]
	s_waitcnt lgkmcnt(0)
	v_mfma_f32_16x16x32_bf16 v[68:71], v[144:147], v[242:245], v[68:71]
	v_mfma_f32_16x16x32_bf16 v[76:79], v[148:151], v[242:245], v[76:79]
	global_load_dwordx4 v[144:147], v[248:249], off
	global_load_dwordx4 v[148:151], v[248:249], off offset:256
	s_waitcnt vmcnt(6)
	s_barrier
	s_add_i32 s9, s3, 4
	s_lshl_b32 s96, s9, 13
	s_add_i32 m0, vcc_lo, 8192
	v_lshl_add_u64 v[160:161], v[188:189], 0, s[96:97]
	global_load_lds_dwordx4 v[160:161], off
	global_load_lds_dwordx4 v[160:161], off offset:1024
	ds_read_b128 v[196:199], v246 offset:16384
	ds_read_b128 v[200:203], v246 offset:17408
	ds_read_b128 v[204:207], v246 offset:18432
	ds_read_b128 v[242:245], v246 offset:19456
	s_add_i32 s9, s3, 4
	s_lshl_b32 s96, s9, 11
	v_lshl_add_u64 v[248:249], v[184:185], 0, s[96:97]
	v_lshl_add_u64 v[250:251], v[186:187], 0, s[96:97]
	s_waitcnt vmcnt(6) lgkmcnt(3)
	v_mfma_f32_16x16x32_bf16 v[112:115], v[128:131], v[196:199], v[112:115]
	v_mfma_f32_16x16x32_bf16 v[120:123], v[132:135], v[196:199], v[120:123]
	ds_read_b128 v[196:199], v246 offset:20480
	s_waitcnt lgkmcnt(3)
	v_mfma_f32_16x16x32_bf16 v[116:119], v[128:131], v[200:203], v[116:119]
	v_mfma_f32_16x16x32_bf16 v[124:127], v[132:135], v[200:203], v[124:127]
	ds_read_b128 v[200:203], v246 offset:21504
	s_waitcnt lgkmcnt(3)
	v_mfma_f32_16x16x32_bf16 v[96:99], v[128:131], v[204:207], v[96:99]
	v_mfma_f32_16x16x32_bf16 v[104:107], v[132:135], v[204:207], v[104:107]
	ds_read_b128 v[204:207], v246 offset:22528
	s_waitcnt lgkmcnt(3)
	v_mfma_f32_16x16x32_bf16 v[100:103], v[128:131], v[242:245], v[100:103]
	v_mfma_f32_16x16x32_bf16 v[108:111], v[132:135], v[242:245], v[108:111]
	ds_read_b128 v[242:245], v246 offset:23552
	s_waitcnt lgkmcnt(3)
	v_mfma_f32_16x16x32_bf16 v[80:83], v[128:131], v[196:199], v[80:83]
	v_mfma_f32_16x16x32_bf16 v[88:91], v[132:135], v[196:199], v[88:91]
	s_waitcnt lgkmcnt(2)
	v_mfma_f32_16x16x32_bf16 v[84:87], v[128:131], v[200:203], v[84:87]
	v_mfma_f32_16x16x32_bf16 v[92:95], v[132:135], v[200:203], v[92:95]
	s_waitcnt lgkmcnt(1)
	v_mfma_f32_16x16x32_bf16 v[64:67], v[128:131], v[204:207], v[64:67]
	v_mfma_f32_16x16x32_bf16 v[72:75], v[132:135], v[204:207], v[72:75]
	s_waitcnt lgkmcnt(0)
	v_mfma_f32_16x16x32_bf16 v[68:71], v[128:131], v[242:245], v[68:71]
	v_mfma_f32_16x16x32_bf16 v[76:79], v[132:135], v[242:245], v[76:79]
	global_load_dwordx4 v[128:131], v[248:249], off
	global_load_dwordx4 v[132:135], v[248:249], off offset:256
	s_waitcnt vmcnt(6)
	s_barrier
	s_add_i32 s9, s3, 5
	s_lshl_b32 s96, s9, 13
	s_add_i32 m0, vcc_lo, 16384
	v_lshl_add_u64 v[160:161], v[188:189], 0, s[96:97]
	global_load_lds_dwordx4 v[160:161], off
	global_load_lds_dwordx4 v[160:161], off offset:1024
	ds_read_b128 v[196:199], v246 offset:0
	ds_read_b128 v[200:203], v246 offset:1024
	ds_read_b128 v[204:207], v246 offset:2048
	ds_read_b128 v[242:245], v246 offset:3072
	s_add_i32 s9, s3, 5
	s_lshl_b32 s96, s9, 11
	v_lshl_add_u64 v[248:249], v[184:185], 0, s[96:97]
	v_lshl_add_u64 v[250:251], v[186:187], 0, s[96:97]
	s_waitcnt vmcnt(6) lgkmcnt(3)
	v_mfma_f32_16x16x32_bf16 v[112:115], v[144:147], v[196:199], v[112:115]
	v_mfma_f32_16x16x32_bf16 v[120:123], v[148:151], v[196:199], v[120:123]
	ds_read_b128 v[196:199], v246 offset:4096
	s_waitcnt lgkmcnt(3)
	v_mfma_f32_16x16x32_bf16 v[116:119], v[144:147], v[200:203], v[116:119]
	v_mfma_f32_16x16x32_bf16 v[124:127], v[148:151], v[200:203], v[124:127]
	ds_read_b128 v[200:203], v246 offset:5120
	s_waitcnt lgkmcnt(3)
	v_mfma_f32_16x16x32_bf16 v[96:99], v[144:147], v[204:207], v[96:99]
	v_mfma_f32_16x16x32_bf16 v[104:107], v[148:151], v[204:207], v[104:107]
	ds_read_b128 v[204:207], v246 offset:6144
	s_waitcnt lgkmcnt(3)
	v_mfma_f32_16x16x32_bf16 v[100:103], v[144:147], v[242:245], v[100:103]
	v_mfma_f32_16x16x32_bf16 v[108:111], v[148:151], v[242:245], v[108:111]
	ds_read_b128 v[242:245], v246 offset:7168
	s_waitcnt lgkmcnt(3)
	v_mfma_f32_16x16x32_bf16 v[80:83], v[144:147], v[196:199], v[80:83]
	v_mfma_f32_16x16x32_bf16 v[88:91], v[148:151], v[196:199], v[88:91]
	s_waitcnt lgkmcnt(2)
	v_mfma_f32_16x16x32_bf16 v[84:87], v[144:147], v[200:203], v[84:87]
	v_mfma_f32_16x16x32_bf16 v[92:95], v[148:151], v[200:203], v[92:95]
	s_waitcnt lgkmcnt(1)
	v_mfma_f32_16x16x32_bf16 v[64:67], v[144:147], v[204:207], v[64:67]
	v_mfma_f32_16x16x32_bf16 v[72:75], v[148:151], v[204:207], v[72:75]
	s_waitcnt lgkmcnt(0)
	v_mfma_f32_16x16x32_bf16 v[68:71], v[144:147], v[242:245], v[68:71]
	v_mfma_f32_16x16x32_bf16 v[76:79], v[148:151], v[242:245], v[76:79]
	global_load_dwordx4 v[144:147], v[248:249], off
	global_load_dwordx4 v[148:151], v[248:249], off offset:256
	s_waitcnt vmcnt(6)
	s_barrier
	s_add_i32 s9, s3, 6
	s_lshl_b32 s96, s9, 13
	s_mov_b32 m0, vcc_lo
	v_lshl_add_u64 v[160:161], v[188:189], 0, s[96:97]
	global_load_lds_dwordx4 v[160:161], off
	global_load_lds_dwordx4 v[160:161], off offset:1024
	ds_read_b128 v[196:199], v246 offset:8192
	ds_read_b128 v[200:203], v246 offset:9216
	ds_read_b128 v[204:207], v246 offset:10240
	ds_read_b128 v[242:245], v246 offset:11264
	s_add_i32 s9, s3, 6
	s_lshl_b32 s96, s9, 11
	v_lshl_add_u64 v[248:249], v[184:185], 0, s[96:97]
	v_lshl_add_u64 v[250:251], v[186:187], 0, s[96:97]
	s_waitcnt vmcnt(6) lgkmcnt(3)
	v_mfma_f32_16x16x32_bf16 v[112:115], v[128:131], v[196:199], v[112:115]
	v_mfma_f32_16x16x32_bf16 v[120:123], v[132:135], v[196:199], v[120:123]
	ds_read_b128 v[196:199], v246 offset:12288
	s_waitcnt lgkmcnt(3)
	v_mfma_f32_16x16x32_bf16 v[116:119], v[128:131], v[200:203], v[116:119]
	v_mfma_f32_16x16x32_bf16 v[124:127], v[132:135], v[200:203], v[124:127]
	ds_read_b128 v[200:203], v246 offset:13312
	s_waitcnt lgkmcnt(3)
	v_mfma_f32_16x16x32_bf16 v[96:99], v[128:131], v[204:207], v[96:99]
	v_mfma_f32_16x16x32_bf16 v[104:107], v[132:135], v[204:207], v[104:107]
	ds_read_b128 v[204:207], v246 offset:14336
	s_waitcnt lgkmcnt(3)
	v_mfma_f32_16x16x32_bf16 v[100:103], v[128:131], v[242:245], v[100:103]
	v_mfma_f32_16x16x32_bf16 v[108:111], v[132:135], v[242:245], v[108:111]
	ds_read_b128 v[242:245], v246 offset:15360
	s_waitcnt lgkmcnt(3)
	v_mfma_f32_16x16x32_bf16 v[80:83], v[128:131], v[196:199], v[80:83]
	v_mfma_f32_16x16x32_bf16 v[88:91], v[132:135], v[196:199], v[88:91]
	s_waitcnt lgkmcnt(2)
	v_mfma_f32_16x16x32_bf16 v[84:87], v[128:131], v[200:203], v[84:87]
	v_mfma_f32_16x16x32_bf16 v[92:95], v[132:135], v[200:203], v[92:95]
	s_waitcnt lgkmcnt(1)
	v_mfma_f32_16x16x32_bf16 v[64:67], v[128:131], v[204:207], v[64:67]
	v_mfma_f32_16x16x32_bf16 v[72:75], v[132:135], v[204:207], v[72:75]
	s_waitcnt lgkmcnt(0)
	v_mfma_f32_16x16x32_bf16 v[68:71], v[128:131], v[242:245], v[68:71]
	v_mfma_f32_16x16x32_bf16 v[76:79], v[132:135], v[242:245], v[76:79]
	global_load_dwordx4 v[128:131], v[248:249], off
	global_load_dwordx4 v[132:135], v[248:249], off offset:256
	s_waitcnt vmcnt(6)
	s_barrier
	s_add_i32 s9, s3, 7
	s_lshl_b32 s96, s9, 13
	s_add_i32 m0, vcc_lo, 8192
	v_lshl_add_u64 v[160:161], v[188:189], 0, s[96:97]
	global_load_lds_dwordx4 v[160:161], off
	global_load_lds_dwordx4 v[160:161], off offset:1024
	ds_read_b128 v[196:199], v246 offset:16384
	ds_read_b128 v[200:203], v246 offset:17408
	ds_read_b128 v[204:207], v246 offset:18432
	ds_read_b128 v[242:245], v246 offset:19456
	s_add_i32 s9, s3, 7
	s_lshl_b32 s96, s9, 11
	v_lshl_add_u64 v[248:249], v[184:185], 0, s[96:97]
	v_lshl_add_u64 v[250:251], v[186:187], 0, s[96:97]
	s_waitcnt vmcnt(6) lgkmcnt(3)
	v_mfma_f32_16x16x32_bf16 v[112:115], v[144:147], v[196:199], v[112:115]
	v_mfma_f32_16x16x32_bf16 v[120:123], v[148:151], v[196:199], v[120:123]
	ds_read_b128 v[196:199], v246 offset:20480
	s_waitcnt lgkmcnt(3)
	v_mfma_f32_16x16x32_bf16 v[116:119], v[144:147], v[200:203], v[116:119]
	v_mfma_f32_16x16x32_bf16 v[124:127], v[148:151], v[200:203], v[124:127]
	ds_read_b128 v[200:203], v246 offset:21504
	s_waitcnt lgkmcnt(3)
	v_mfma_f32_16x16x32_bf16 v[96:99], v[144:147], v[204:207], v[96:99]
	v_mfma_f32_16x16x32_bf16 v[104:107], v[148:151], v[204:207], v[104:107]
	ds_read_b128 v[204:207], v246 offset:22528
	s_waitcnt lgkmcnt(3)
	v_mfma_f32_16x16x32_bf16 v[100:103], v[144:147], v[242:245], v[100:103]
	v_mfma_f32_16x16x32_bf16 v[108:111], v[148:151], v[242:245], v[108:111]
	ds_read_b128 v[242:245], v246 offset:23552
	s_waitcnt lgkmcnt(3)
	v_mfma_f32_16x16x32_bf16 v[80:83], v[144:147], v[196:199], v[80:83]
	v_mfma_f32_16x16x32_bf16 v[88:91], v[148:151], v[196:199], v[88:91]
	s_waitcnt lgkmcnt(2)
	v_mfma_f32_16x16x32_bf16 v[84:87], v[144:147], v[200:203], v[84:87]
	v_mfma_f32_16x16x32_bf16 v[92:95], v[148:151], v[200:203], v[92:95]
	s_waitcnt lgkmcnt(1)
	v_mfma_f32_16x16x32_bf16 v[64:67], v[144:147], v[204:207], v[64:67]
	v_mfma_f32_16x16x32_bf16 v[72:75], v[148:151], v[204:207], v[72:75]
	s_waitcnt lgkmcnt(0)
	v_mfma_f32_16x16x32_bf16 v[68:71], v[144:147], v[242:245], v[68:71]
	v_mfma_f32_16x16x32_bf16 v[76:79], v[148:151], v[242:245], v[76:79]
	global_load_dwordx4 v[144:147], v[248:249], off
	global_load_dwordx4 v[148:151], v[248:249], off offset:256
	s_waitcnt vmcnt(6)
	s_barrier
	s_add_i32 s3, s3, 6
	s_cmp_lt_u32 s3, 30
	s_cbranch_scc1 .Lg16_outh_k
	ds_read_b128 v[196:199], v246 offset:0
	ds_read_b128 v[200:203], v246 offset:1024
	ds_read_b128 v[204:207], v246 offset:2048
	ds_read_b128 v[242:245], v246 offset:3072
	s_waitcnt vmcnt(4) lgkmcnt(3)
	v_mfma_f32_16x16x32_bf16 v[112:115], v[128:131], v[196:199], v[112:115]
	v_mfma_f32_16x16x32_bf16 v[120:123], v[132:135], v[196:199], v[120:123]
	ds_read_b128 v[196:199], v246 offset:4096
	s_waitcnt lgkmcnt(3)
	v_mfma_f32_16x16x32_bf16 v[116:119], v[128:131], v[200:203], v[116:119]
	v_mfma_f32_16x16x32_bf16 v[124:127], v[132:135], v[200:203], v[124:127]
	ds_read_b128 v[200:203], v246 offset:5120
	s_waitcnt lgkmcnt(3)
	v_mfma_f32_16x16x32_bf16 v[96:99], v[128:131], v[204:207], v[96:99]
	v_mfma_f32_16x16x32_bf16 v[104:107], v[132:135], v[204:207], v[104:107]
	ds_read_b128 v[204:207], v246 offset:6144
	s_waitcnt lgkmcnt(3)
	v_mfma_f32_16x16x32_bf16 v[100:103], v[128:131], v[242:245], v[100:103]
	v_mfma_f32_16x16x32_bf16 v[108:111], v[132:135], v[242:245], v[108:111]
	ds_read_b128 v[242:245], v246 offset:7168
	s_waitcnt lgkmcnt(3)
	v_mfma_f32_16x16x32_bf16 v[80:83], v[128:131], v[196:199], v[80:83]
	v_mfma_f32_16x16x32_bf16 v[88:91], v[132:135], v[196:199], v[88:91]
	s_waitcnt lgkmcnt(2)
	v_mfma_f32_16x16x32_bf16 v[84:87], v[128:131], v[200:203], v[84:87]
	v_mfma_f32_16x16x32_bf16 v[92:95], v[132:135], v[200:203], v[92:95]
	s_waitcnt lgkmcnt(1)
	v_mfma_f32_16x16x32_bf16 v[64:67], v[128:131], v[204:207], v[64:67]
	v_mfma_f32_16x16x32_bf16 v[72:75], v[132:135], v[204:207], v[72:75]
	s_waitcnt lgkmcnt(0)
	v_mfma_f32_16x16x32_bf16 v[68:71], v[128:131], v[242:245], v[68:71]
	v_mfma_f32_16x16x32_bf16 v[76:79], v[132:135], v[242:245], v[76:79]
	s_waitcnt vmcnt(2)
	s_barrier
	ds_read_b128 v[196:199], v246 offset:8192
	ds_read_b128 v[200:203], v246 offset:9216
	ds_read_b128 v[204:207], v246 offset:10240
	ds_read_b128 v[242:245], v246 offset:11264
	s_waitcnt vmcnt(0) lgkmcnt(3)
	v_mfma_f32_16x16x32_bf16 v[112:115], v[144:147], v[196:199], v[112:115]
	v_mfma_f32_16x16x32_bf16 v[120:123], v[148:151], v[196:199], v[120:123]
	ds_read_b128 v[196:199], v246 offset:12288
	s_waitcnt lgkmcnt(3)
	v_mfma_f32_16x16x32_bf16 v[116:119], v[144:147], v[200:203], v[116:119]
	v_mfma_f32_16x16x32_bf16 v[124:127], v[148:151], v[200:203], v[124:127]
	ds_read_b128 v[200:203], v246 offset:13312
	s_waitcnt lgkmcnt(3)
	v_mfma_f32_16x16x32_bf16 v[96:99], v[144:147], v[204:207], v[96:99]
	v_mfma_f32_16x16x32_bf16 v[104:107], v[148:151], v[204:207], v[104:107]
	ds_read_b128 v[204:207], v246 offset:14336
	s_waitcnt lgkmcnt(3)
	v_mfma_f32_16x16x32_bf16 v[100:103], v[144:147], v[242:245], v[100:103]
	v_mfma_f32_16x16x32_bf16 v[108:111], v[148:151], v[242:245], v[108:111]
	ds_read_b128 v[242:245], v246 offset:15360
	v_permlane16_swap_b32_e32 v112, v116
	v_permlane16_swap_b32_e32 v113, v117
	v_permlane16_swap_b32_e32 v114, v118
	v_permlane16_swap_b32_e32 v115, v119
	v_permlane16_swap_b32_e32 v120, v124
	v_permlane16_swap_b32_e32 v121, v125
	v_permlane16_swap_b32_e32 v122, v126
	v_permlane16_swap_b32_e32 v123, v127
	v_permlane16_swap_b32_e32 v48, v52
	v_permlane16_swap_b32_e32 v49, v53
	v_permlane16_swap_b32_e32 v50, v54
	v_permlane16_swap_b32_e32 v51, v55
	v_permlane16_swap_b32_e32 v56, v60
	v_permlane16_swap_b32_e32 v57, v61
	v_permlane16_swap_b32_e32 v58, v62
	v_permlane16_swap_b32_e32 v59, v63
	v_permlane32_swap_b32_e32 v112, v116
	v_permlane32_swap_b32_e32 v113, v117
	v_permlane32_swap_b32_e32 v114, v118
	v_permlane32_swap_b32_e32 v115, v119
	v_permlane32_swap_b32_e32 v120, v124
	v_permlane32_swap_b32_e32 v121, v125
	v_permlane32_swap_b32_e32 v122, v126
	v_permlane32_swap_b32_e32 v123, v127
	v_permlane32_swap_b32_e32 v48, v52
	v_permlane32_swap_b32_e32 v49, v53
	v_permlane32_swap_b32_e32 v50, v54
	v_permlane32_swap_b32_e32 v51, v55
	v_permlane32_swap_b32_e32 v56, v60
	v_permlane32_swap_b32_e32 v57, v61
	v_permlane32_swap_b32_e32 v58, v62
	v_permlane32_swap_b32_e32 v59, v63
	s_waitcnt lgkmcnt(3)
	v_mfma_f32_16x16x32_bf16 v[80:83], v[144:147], v[196:199], v[80:83]
	v_mfma_f32_16x16x32_bf16 v[88:91], v[148:151], v[196:199], v[88:91]
	s_waitcnt lgkmcnt(2)
	v_mfma_f32_16x16x32_bf16 v[84:87], v[144:147], v[200:203], v[84:87]
	v_mfma_f32_16x16x32_bf16 v[92:95], v[148:151], v[200:203], v[92:95]
	v_permlane16_swap_b32_e32 v96, v100
	v_permlane16_swap_b32_e32 v97, v101
	v_permlane16_swap_b32_e32 v98, v102
	v_permlane16_swap_b32_e32 v99, v103
	v_permlane16_swap_b32_e32 v104, v108
	v_permlane16_swap_b32_e32 v105, v109
	v_permlane16_swap_b32_e32 v106, v110
	v_permlane16_swap_b32_e32 v107, v111
	v_permlane16_swap_b32_e32 v32, v36
	v_permlane16_swap_b32_e32 v33, v37
	v_permlane16_swap_b32_e32 v34, v38
	v_permlane16_swap_b32_e32 v35, v39
	v_permlane16_swap_b32_e32 v40, v44
	v_permlane16_swap_b32_e32 v41, v45
	v_permlane16_swap_b32_e32 v42, v46
	v_permlane16_swap_b32_e32 v43, v47
	v_permlane32_swap_b32_e32 v96, v100
	v_permlane32_swap_b32_e32 v97, v101
	v_permlane32_swap_b32_e32 v98, v102
	v_permlane32_swap_b32_e32 v99, v103
	v_permlane32_swap_b32_e32 v104, v108
	v_permlane32_swap_b32_e32 v105, v109
	v_permlane32_swap_b32_e32 v106, v110
	v_permlane32_swap_b32_e32 v107, v111
	v_permlane32_swap_b32_e32 v32, v36
	v_permlane32_swap_b32_e32 v33, v37
	v_permlane32_swap_b32_e32 v34, v38
	v_permlane32_swap_b32_e32 v35, v39
	v_permlane32_swap_b32_e32 v40, v44
	v_permlane32_swap_b32_e32 v41, v45
	v_permlane32_swap_b32_e32 v42, v46
	v_permlane32_swap_b32_e32 v43, v47
	s_waitcnt lgkmcnt(1)
	v_mfma_f32_16x16x32_bf16 v[64:67], v[144:147], v[204:207], v[64:67]
	v_mfma_f32_16x16x32_bf16 v[72:75], v[148:151], v[204:207], v[72:75]
	s_waitcnt lgkmcnt(0)
	v_mfma_f32_16x16x32_bf16 v[68:71], v[144:147], v[242:245], v[68:71]
	v_mfma_f32_16x16x32_bf16 v[76:79], v[148:151], v[242:245], v[76:79]
	v_permlane16_swap_b32_e32 v80, v84
	v_permlane16_swap_b32_e32 v81, v85
	v_permlane16_swap_b32_e32 v82, v86
	v_permlane16_swap_b32_e32 v83, v87
	v_permlane16_swap_b32_e32 v88, v92
	v_permlane16_swap_b32_e32 v89, v93
	v_permlane16_swap_b32_e32 v90, v94
	v_permlane16_swap_b32_e32 v91, v95
	v_permlane16_swap_b32_e32 v16, v20
	v_permlane16_swap_b32_e32 v17, v21
	v_permlane16_swap_b32_e32 v18, v22
	v_permlane16_swap_b32_e32 v19, v23
	v_permlane16_swap_b32_e32 v24, v28
	v_permlane16_swap_b32_e32 v25, v29
	v_permlane16_swap_b32_e32 v26, v30
	v_permlane16_swap_b32_e32 v27, v31
	v_permlane32_swap_b32_e32 v80, v84
	v_permlane32_swap_b32_e32 v81, v85
	v_permlane32_swap_b32_e32 v82, v86
	v_permlane32_swap_b32_e32 v83, v87
	v_permlane32_swap_b32_e32 v88, v92
	v_permlane32_swap_b32_e32 v89, v93
	v_permlane32_swap_b32_e32 v90, v94
	v_permlane32_swap_b32_e32 v91, v95
	v_permlane32_swap_b32_e32 v16, v20
	v_permlane32_swap_b32_e32 v17, v21
	v_permlane32_swap_b32_e32 v18, v22
	v_permlane32_swap_b32_e32 v19, v23
	v_permlane32_swap_b32_e32 v24, v28
	v_permlane32_swap_b32_e32 v25, v29
	v_permlane32_swap_b32_e32 v26, v30
	v_permlane32_swap_b32_e32 v27, v31
	s_barrier
	s_nop 7
	v_permlane16_swap_b32_e32 v64, v68
	v_permlane16_swap_b32_e32 v65, v69
	v_permlane16_swap_b32_e32 v66, v70
	v_permlane16_swap_b32_e32 v67, v71
	v_permlane16_swap_b32_e32 v72, v76
	v_permlane16_swap_b32_e32 v73, v77
	v_permlane16_swap_b32_e32 v74, v78
	v_permlane16_swap_b32_e32 v75, v79
	v_permlane16_swap_b32_e32 v0, v4
	v_permlane16_swap_b32_e32 v1, v5
	v_permlane16_swap_b32_e32 v2, v6
	v_permlane16_swap_b32_e32 v3, v7
	v_permlane16_swap_b32_e32 v8, v12
	v_permlane16_swap_b32_e32 v9, v13
	v_permlane16_swap_b32_e32 v10, v14
	v_permlane16_swap_b32_e32 v11, v15
	v_permlane32_swap_b32_e32 v64, v68
	v_permlane32_swap_b32_e32 v65, v69
	v_permlane32_swap_b32_e32 v66, v70
	v_permlane32_swap_b32_e32 v67, v71
	v_permlane32_swap_b32_e32 v72, v76
	v_permlane32_swap_b32_e32 v73, v77
	v_permlane32_swap_b32_e32 v74, v78
	v_permlane32_swap_b32_e32 v75, v79
	v_permlane32_swap_b32_e32 v0, v4
	v_permlane32_swap_b32_e32 v1, v5
	v_permlane32_swap_b32_e32 v2, v6
	v_permlane32_swap_b32_e32 v3, v7
	v_permlane32_swap_b32_e32 v8, v12
	v_permlane32_swap_b32_e32 v9, v13
	v_permlane32_swap_b32_e32 v10, v14
	v_permlane32_swap_b32_e32 v11, v15
	s_waitcnt vmcnt(0)
	s_waitcnt vmcnt(0)
	v_and_b32_e32 v188, 63, v179
	v_lshrrev_b32_e32 v189, 6, v179
	v_mul_u32_u24_e32 v249, 0x2400, v189
	v_mov_b32_e32 v250, v249
	v_lshrrev_b32_e32 v251, 5, v188
	v_mul_u32_u24_e32 v251, 0x440, v251
	v_add_u32_e32 v249, v249, v251
	v_and_b32_e32 v251, 31, v188
	v_lshl_add_u32 v249, v251, 2, v249
	v_lshrrev_b32_e32 v237, 4, v188
	v_mul_u32_u24_e32 v251, 0x110, v237
	v_add_u32_e32 v250, v250, v251
	v_and_b32_e32 v251, 15, v188
	v_lshlrev_b32_e32 v251, 4, v251
	v_add_u32_e32 v250, v250, v251
	v_lshl_add_u32 v237, v189, 6, v237
	v_lshl_add_u32 v237, v237, 12, v251
	v_add_u32_e32 v238, 16384, v237
	v_add_u32_e32 v239, 32768, v237
	v_add_u32_e32 v240, 49152, v237
	v_add_u32_e32 v241, 65536, v237
	v_add_u32_e32 v242, 81920, v237
	v_add_u32_e32 v243, 98304, v237
	v_add_u32_e32 v248, 114688, v237
	s_lshl_b32 s16, s8, 8
	s_lshl_b32 s18, s2, 9
	s_lshr_b32 s19, s8, 4
	v_readlane_b32 s12, v254, 38
	v_readlane_b32 s13, v254, 37
	v_readlane_b32 s14, v253, 46
	v_readlane_b32 s15, v253, 47
	v_readlane_b32 s22, v254, 40
	v_readlane_b32 s23, v254, 39
	s_add_i32 s17, s16, 0xffff8000
	s_cmpk_lt_u32 s8, 0x80
	s_cselect_b32 s12, s12, s22
	s_cselect_b32 s13, s13, s23
	s_cselect_b32 s14, s14, s62
	s_cselect_b32 s15, s15, s63
	s_cselect_b32 s19, s19, 8
	s_cselect_b32 s16, s16, s17
	s_mov_b32 s17, 0
	s_lshl_b64 s[16:17], s[16:17], 12
	s_add_u32 s16, s16, s18
	s_addc_u32 s17, s17, 0
	s_add_u32 s12, s12, s16
	s_addc_u32 s13, s13, s17
	s_add_u32 s14, s14, s16
	s_addc_u32 s15, s15, s17
	s_mul_i32 s19, s19, 0x6000
	s_add_u32 s20, s0, s19
	s_addc_u32 s21, s1, 0
	s_add_u32 s20, s20, s18
	s_addc_u32 s21, s21, 0
	s_cmp_eq_u32 s101, 1
	s_cbranch_scc0 .Lre_outh_h0
	s_add_u32 s12, s12, 0x20000
	s_addc_u32 s13, s13, 0
	s_add_u32 s14, s14, 0x20000
	s_addc_u32 s15, s15, 0
.Lre_outh_h0:
	global_load_dwordx4 v[244:247], v251, s[20:21]
	global_load_dwordx4 v[160:163], v237, s[12:13]
	global_load_dwordx4 v[164:167], v238, s[12:13]
	global_load_dwordx4 v[168:171], v239, s[12:13]
	global_load_dwordx4 v[172:175], v240, s[12:13]
	global_load_dwordx4 v[196:199], v241, s[12:13]
	global_load_dwordx4 v[200:203], v242, s[12:13]
	global_load_dwordx4 v[204:207], v243, s[12:13]
	global_load_dwordx4 v[184:187], v248, s[12:13]
	ds_write_b32 v249, v112
	ds_write_b32 v249, v113 offset:272
	ds_write_b32 v249, v114 offset:544
	ds_write_b32 v249, v115 offset:816
	ds_write_b32 v249, v116 offset:2176
	ds_write_b32 v249, v117 offset:2448
	ds_write_b32 v249, v118 offset:2720
	ds_write_b32 v249, v119 offset:2992
	ds_write_b32 v249, v120 offset:4352
	ds_write_b32 v249, v121 offset:4624
	ds_write_b32 v249, v122 offset:4896
	ds_write_b32 v249, v123 offset:5168
	ds_write_b32 v249, v124 offset:6528
	ds_write_b32 v249, v125 offset:6800
	ds_write_b32 v249, v126 offset:7072
	ds_write_b32 v249, v127 offset:7344
	ds_write_b32 v249, v96 offset:128
	ds_write_b32 v249, v97 offset:400
	ds_write_b32 v249, v98 offset:672
	ds_write_b32 v249, v99 offset:944
	ds_write_b32 v249, v100 offset:2304
	ds_write_b32 v249, v101 offset:2576
	ds_write_b32 v249, v102 offset:2848
	ds_write_b32 v249, v103 offset:3120
	ds_write_b32 v249, v104 offset:4480
	ds_write_b32 v249, v105 offset:4752
	ds_write_b32 v249, v106 offset:5024
	ds_write_b32 v249, v107 offset:5296
	ds_write_b32 v249, v108 offset:6656
	ds_write_b32 v249, v109 offset:6928
	ds_write_b32 v249, v110 offset:7200
	ds_write_b32 v249, v111 offset:7472
	s_waitcnt lgkmcnt(0)
	ds_read_b128 v[128:131], v250
	ds_read_b128 v[132:135], v250 offset:1088
	ds_read_b128 v[136:139], v250 offset:2176
	ds_read_b128 v[140:143], v250 offset:3264
	ds_read_b128 v[144:147], v250 offset:4352
	ds_read_b128 v[148:151], v250 offset:5440
	ds_read_b128 v[152:155], v250 offset:6528
	ds_read_b128 v[156:159], v250 offset:7616
	s_waitcnt vmcnt(7) lgkmcnt(7)
	v_fma_f32 v128, v244, v128, v160
	v_fma_f32 v129, v245, v129, v161
	v_fma_f32 v130, v246, v130, v162
	v_fma_f32 v131, v247, v131, v163
	global_store_dwordx4 v237, v[128:131], s[14:15]
	s_waitcnt vmcnt(7) lgkmcnt(6)
	v_fma_f32 v132, v244, v132, v164
	v_fma_f32 v133, v245, v133, v165
	v_fma_f32 v134, v246, v134, v166
	v_fma_f32 v135, v247, v135, v167
	global_store_dwordx4 v238, v[132:135], s[14:15]
	s_waitcnt vmcnt(7) lgkmcnt(5)
	v_fma_f32 v136, v244, v136, v168
	v_fma_f32 v137, v245, v137, v169
	v_fma_f32 v138, v246, v138, v170
	v_fma_f32 v139, v247, v139, v171
	global_store_dwordx4 v239, v[136:139], s[14:15]
	s_waitcnt vmcnt(7) lgkmcnt(4)
	v_fma_f32 v140, v244, v140, v172
	v_fma_f32 v141, v245, v141, v173
	v_fma_f32 v142, v246, v142, v174
	v_fma_f32 v143, v247, v143, v175
	global_store_dwordx4 v240, v[140:143], s[14:15]
	s_waitcnt vmcnt(7) lgkmcnt(3)
	v_fma_f32 v144, v244, v144, v196
	v_fma_f32 v145, v245, v145, v197
	v_fma_f32 v146, v246, v146, v198
	v_fma_f32 v147, v247, v147, v199
	global_store_dwordx4 v241, v[144:147], s[14:15]
	s_waitcnt vmcnt(7) lgkmcnt(2)
	v_fma_f32 v148, v244, v148, v200
	v_fma_f32 v149, v245, v149, v201
	v_fma_f32 v150, v246, v150, v202
	v_fma_f32 v151, v247, v151, v203
	global_store_dwordx4 v242, v[148:151], s[14:15]
	s_waitcnt vmcnt(7) lgkmcnt(1)
	v_fma_f32 v152, v244, v152, v204
	v_fma_f32 v153, v245, v153, v205
	v_fma_f32 v154, v246, v154, v206
	v_fma_f32 v155, v247, v155, v207
	global_store_dwordx4 v243, v[152:155], s[14:15]
	s_waitcnt vmcnt(7) lgkmcnt(0)
	v_fma_f32 v156, v244, v156, v184
	v_fma_f32 v157, v245, v157, v185
	v_fma_f32 v158, v246, v158, v186
	v_fma_f32 v159, v247, v159, v187
	global_store_dwordx4 v248, v[156:159], s[14:15]
	global_load_dwordx4 v[244:247], v251, s[20:21] offset:256
	global_load_dwordx4 v[160:163], v237, s[12:13] offset:256
	global_load_dwordx4 v[164:167], v238, s[12:13] offset:256
	global_load_dwordx4 v[168:171], v239, s[12:13] offset:256
	global_load_dwordx4 v[172:175], v240, s[12:13] offset:256
	global_load_dwordx4 v[196:199], v241, s[12:13] offset:256
	global_load_dwordx4 v[200:203], v242, s[12:13] offset:256
	global_load_dwordx4 v[204:207], v243, s[12:13] offset:256
	global_load_dwordx4 v[184:187], v248, s[12:13] offset:256
	ds_write_b32 v249, v80
	ds_write_b32 v249, v81 offset:272
	ds_write_b32 v249, v82 offset:544
	ds_write_b32 v249, v83 offset:816
	ds_write_b32 v249, v84 offset:2176
	ds_write_b32 v249, v85 offset:2448
	ds_write_b32 v249, v86 offset:2720
	ds_write_b32 v249, v87 offset:2992
	ds_write_b32 v249, v88 offset:4352
	ds_write_b32 v249, v89 offset:4624
	ds_write_b32 v249, v90 offset:4896
	ds_write_b32 v249, v91 offset:5168
	ds_write_b32 v249, v92 offset:6528
	ds_write_b32 v249, v93 offset:6800
	ds_write_b32 v249, v94 offset:7072
	ds_write_b32 v249, v95 offset:7344
	ds_write_b32 v249, v64 offset:128
	ds_write_b32 v249, v65 offset:400
	ds_write_b32 v249, v66 offset:672
	ds_write_b32 v249, v67 offset:944
	ds_write_b32 v249, v68 offset:2304
	ds_write_b32 v249, v69 offset:2576
	ds_write_b32 v249, v70 offset:2848
	ds_write_b32 v249, v71 offset:3120
	ds_write_b32 v249, v72 offset:4480
	ds_write_b32 v249, v73 offset:4752
	ds_write_b32 v249, v74 offset:5024
	ds_write_b32 v249, v75 offset:5296
	ds_write_b32 v249, v76 offset:6656
	ds_write_b32 v249, v77 offset:6928
	ds_write_b32 v249, v78 offset:7200
	ds_write_b32 v249, v79 offset:7472
	s_waitcnt lgkmcnt(0)
	ds_read_b128 v[128:131], v250
	ds_read_b128 v[132:135], v250 offset:1088
	ds_read_b128 v[136:139], v250 offset:2176
	ds_read_b128 v[140:143], v250 offset:3264
	ds_read_b128 v[144:147], v250 offset:4352
	ds_read_b128 v[148:151], v250 offset:5440
	ds_read_b128 v[152:155], v250 offset:6528
	ds_read_b128 v[156:159], v250 offset:7616
	s_waitcnt vmcnt(7) lgkmcnt(7)
	v_fma_f32 v128, v244, v128, v160
	v_fma_f32 v129, v245, v129, v161
	v_fma_f32 v130, v246, v130, v162
	v_fma_f32 v131, v247, v131, v163
	global_store_dwordx4 v237, v[128:131], s[14:15] offset:256
	s_waitcnt vmcnt(7) lgkmcnt(6)
	v_fma_f32 v132, v244, v132, v164
	v_fma_f32 v133, v245, v133, v165
	v_fma_f32 v134, v246, v134, v166
	v_fma_f32 v135, v247, v135, v167
	global_store_dwordx4 v238, v[132:135], s[14:15] offset:256
	s_waitcnt vmcnt(7) lgkmcnt(5)
	v_fma_f32 v136, v244, v136, v168
	v_fma_f32 v137, v245, v137, v169
	v_fma_f32 v138, v246, v138, v170
	v_fma_f32 v139, v247, v139, v171
	global_store_dwordx4 v239, v[136:139], s[14:15] offset:256
	s_waitcnt vmcnt(7) lgkmcnt(4)
	v_fma_f32 v140, v244, v140, v172
	v_fma_f32 v141, v245, v141, v173
	v_fma_f32 v142, v246, v142, v174
	v_fma_f32 v143, v247, v143, v175
	global_store_dwordx4 v240, v[140:143], s[14:15] offset:256
	s_waitcnt vmcnt(7) lgkmcnt(3)
	v_fma_f32 v144, v244, v144, v196
	v_fma_f32 v145, v245, v145, v197
	v_fma_f32 v146, v246, v146, v198
	v_fma_f32 v147, v247, v147, v199
	global_store_dwordx4 v241, v[144:147], s[14:15] offset:256
	s_waitcnt vmcnt(7) lgkmcnt(2)
	v_fma_f32 v148, v244, v148, v200
	v_fma_f32 v149, v245, v149, v201
	v_fma_f32 v150, v246, v150, v202
	v_fma_f32 v151, v247, v151, v203
	global_store_dwordx4 v242, v[148:151], s[14:15] offset:256
	s_waitcnt vmcnt(7) lgkmcnt(1)
	v_fma_f32 v152, v244, v152, v204
	v_fma_f32 v153, v245, v153, v205
	v_fma_f32 v154, v246, v154, v206
	v_fma_f32 v155, v247, v155, v207
	global_store_dwordx4 v243, v[152:155], s[14:15] offset:256
	s_waitcnt vmcnt(7) lgkmcnt(0)
	v_fma_f32 v156, v244, v156, v184
	v_fma_f32 v157, v245, v157, v185
	v_fma_f32 v158, v246, v158, v186
	v_fma_f32 v159, v247, v159, v187
	global_store_dwordx4 v248, v[156:159], s[14:15] offset:256
	s_waitcnt lgkmcnt(0)
	s_mov_b32 s100, 0
	s_barrier
	s_branch .LBB0_926
.LBB0_926:
	s_waitcnt vmcnt(0) lgkmcnt(0)
	v_mov_b32_e32 v0, v179
	s_barrier
	s_nop 0
	v_cmp_eq_u32_e32 vcc, 0, v0
	s_and_saveexec_b64 s[0:1], vcc
	s_cbranch_execz .LBB0_976
	s_mov_b64 s[2:3], src_shared_base
	v_mov_b32_e32 v181, s3
	s_getreg_b32 s2, hwreg(HW_REG_XCC_ID, 0, 4)
	flat_load_dword v2, v[180:181] sc0 sc1
	s_waitcnt vmcnt(0)
	v_mov_b32_e32 v183, s3
	flat_load_dword v0, v[182:183] sc0 sc1
	s_waitcnt vmcnt(0)
	s_and_b32 s6, s2, 15
	s_waitcnt lgkmcnt(0)
	v_cmp_eq_u32_e32 vcc, 0, v2
	s_and_saveexec_b64 s[2:3], vcc
	s_cbranch_execz .LBB0_936
	s_mov_b32 s7, 0x400000
	s_branch .LBB0_931
